# w1 + LDS-DMA sources as scalar base + 32-bit lane offset (saddr form), bases advanced by SALU, in both attention loops
# speedup vs baseline: 1.0299x; 1.0299x over previous
; __device__ __forceinline__ float fsub_s(float a,float b){float r;asm("v_sub_f32_e32 %0, %1, %2":"=v"(r):"v"(a),"v"(b));return r;}
; #define WAIT_BAR(N) asm volatile("s_waitcnt vmcnt(" #N ") lgkmcnt(0)\n\ts_barrier":::"memory")
;   #define DMA_K(t,slot) glds16(ksrc+(long)(t)*KVBLK*kp,(unsigned)__builtin_amdgcn_readfirstlane(kdst+(slot)))
;   #define DMA_V(t,slot) glds16(vsrc+(long)(t)*KVBLK*vp,(unsigned)__builtin_amdgcn_readfirstlane(vdst+(slot)))
;   #define ROT() do{sl_prev=sl_cur;sl_cur=sl_next;sl_next=(sl_next==(NSLOT-1)*SLOTB)?0:sl_next+SLOTB;}while(0)
;   #define DMA_K(t,slot) glds16(ksrc+(long)(t)*KVBLK*kp,(unsigned)__builtin_amdgcn_readfirstlane(kdst+(slot)))
;   #define DMA_V(t,slot) glds16(vsrc+(long)(t)*KVBLK*vp,(unsigned)__builtin_amdgcn_readfirstlane(vdst+(slot)))
; template<int THRL,bool NOMAX=false> __device__ __forceinline__ void attn_unit_v128(const bf16*Qu,int qp,const bf16*__restrict__ Kh,int kp,const bf16*__restrict__ Vh,int vp,bf16*Ou,int op,int NT,char*shm,int tid_in){
;     ...
;   const bf16*ksrc=Kh+(long)lane*kp+wid*8;
;   const bf16*vsrc=Vh+(long)(16*(wid&3)+(lane>>2))*vp+(wid>>2)*32+(lane&3)*8;
;   const unsigned kdst=lds0+V2_LDS_K+wid*1024, vdst=lds0+V2_LDS_V+wid*1024;
;     ...
;   const int vb0=(int)(lds0+V2_LDS_V)+((lane>>4)&1)*32+(lane&3)*8+(4*hi+((lane&15)>>2))*64;
;   const char*Kbase=shm+V2_LDS_K; bf16x8 kf[8];
;   const lds_cptr shm3=(lds_cptr)shm; const lds_cptr kp0=shm3+V2_LDS_K+hi*1024+r32*16; const lds_cptr vp0=shm3+V2_LDS_V+((lane>>4)&1)*32+(lane&3)*8+(4*hi+((lane&15)>>2))*64;
;   DMA_K(0,0);DMA_V(0,0);DMA_K(1,SLOTB);
;   bf16x8 qr[4];
;   #pragma unroll
;   for(int d0=0;d0<4;++d0)qr[d0]=*reinterpret_cast<const bf16x8*>(&Qw[(long)r32*qp+d0*16+hi*8]);
;   float mhat=0.f,l_reg=0.f;f32x16 o[4];o[0]=f32x16{};o[1]=f32x16{};o[2]=f32x16{};o[3]=f32x16{};
;   const f32x16 zero16=f32x16{};
;   bool resc=false;
;     ...
;   f32x16 pA0,pA1,pB0,pB1;
;   int sl_prev=0,sl_cur=0,sl_next=SLOTB;
;     ...
;   DMA_K(2,2*SLOTB);
;   WAIT_BAR(3);
;   qkt0(pA0,pA1,Kbase,qr,r32,hi);asm volatile("s_nop 15\n\ts_nop 7":"+v"(pA0),"+v"(pA1));
;   START(pA0,pA1);
;   if constexpr(NOMAX){ _Pragma("unroll") for(int r=0;r<16;++r)pA1[r]=__builtin_amdgcn_exp2f(pA1[r]); } else { _Pragma("unroll") for(int r=0;r<16;++r)pA1[r]=__builtin_amdgcn_exp2f(fsub_s(pA1[r],mhat)); }
;   WAIT_BAR(0);
;   DMA_K(3,0);DMA_V(1,SLOTB);
;   ROT();
;   kload8(kf,kp0+sl_cur);
;   WAIT_BAR(3);
.LBB0_795:
	s_and_b64 vcc, exec, s[6:7]
	s_cbranch_vccz .LBB0_839
	v_readlane_b32 s2, v253, 6
	v_mbcnt_lo_u32_b32 v0, -1, 0
	v_mbcnt_hi_u32_b32 v0, -1, v0
	s_mov_b32 s86, 1
	s_waitcnt vmcnt(7)
	v_or_b32_e32 v46, s2, v0
	s_nop 0
	v_readfirstlane_b32 s39, v46
	s_ashr_i32 s38, s39, 6
	s_lshl_b32 s2, s38, 5
	s_ashr_i32 s3, s2, 31
	s_lshl_b64 s[2:3], s[2:3], 10
	v_and_b32_e32 v206, 63, v46
	s_add_u32 s6, s33, s2
	s_addc_u32 s7, s76, s3
	v_lshrrev_b32_e32 v2, 3, v206
	v_lshl_add_u32 v2, s38, 3, v2
	v_lshrrev_b32_e32 v3, 1, v2
	v_xor_b32_e32 v3, v3, v206
	v_and_b32_e32 v3, 7, v3
	v_lshlrev_b32_e32 v2, 10, v2
	v_lshl_add_u32 v0, v3, 4, v2
	v_lshl_add_u64 v[194:195], s[36:37], 0, v[0:1]
	s_lshl_b32 s8, s38, 4
	v_bfe_u32 v0, v46, 2, 4
	v_and_or_b32 v0, s8, 48, v0
	s_ashr_i32 s8, s39, 3
	s_andn2_b32 s8, s8, 31
	v_lshlrev_b32_e32 v0, 10, v0
	s_ashr_i32 s9, s8, 31
	s_lshl_b32 s33, s38, 10
	v_lshl_add_u64 v[2:3], s[34:35], 0, v[0:1]
	v_lshlrev_b32_e32 v209, 3, v46
	s_cmp_lg_u32 0, -1
	v_lshl_add_u64 v[2:3], s[8:9], 1, v[2:3]
	v_and_b32_e32 v211, 24, v209
	s_cselect_b32 s8, 0, 0
	v_lshlrev_b32_e32 v0, 1, v211
	s_add_i32 s33, s33, s8
	s_mov_b32 s8, m0
	s_mov_b32 m0, s33
	s_nop 0
	global_load_lds_dwordx4 v[194:195], off
	s_mov_b32 m0, s8
	v_and_b32_e32 v207, 31, v46
	v_lshl_add_u64 v[196:197], v[2:3], 0, v[0:1]
	s_add_i32 s34, s33, 0x6000
	s_mov_b32 s8, m0
	s_mov_b32 m0, s34
	s_nop 0
	global_load_lds_dwordx4 v[196:197], off
	s_mov_b32 m0, s8
	v_bfe_u32 v208, v46, 5, 1
	v_lshl_add_u64 v[198:199], v[196:197], 0, s[0:1]
	s_add_i32 s8, s33, 0x8000
	s_mov_b32 s9, m0
	s_mov_b32 m0, s8
	s_nop 0
	global_load_lds_dwordx4 v[198:199], off
	s_mov_b32 m0, s9
	s_mov_b64 s[76:77], 0x10000
	v_lshlrev_b32_e32 v0, 10, v207
	v_lshl_add_u64 v[2:3], v[194:195], 0, s[76:77]
	s_add_i32 s8, s33, 0x2000
	s_mov_b32 s9, m0
	s_mov_b32 m0, s8
	s_nop 0
	global_load_lds_dwordx4 v[2:3], off
	s_mov_b32 m0, s9
	v_lshl_or_b32 v0, v208, 4, v0
	global_load_dwordx4 v[154:157], v0, s[6:7]
	global_load_dwordx4 v[150:153], v0, s[6:7] offset:32
	global_load_dwordx4 v[142:145], v0, s[6:7] offset:64
	global_load_dwordx4 v[134:137], v0, s[6:7] offset:96
	s_mov_b64 s[6:7], 0x20000
	v_lshlrev_b32_e32 v0, 7, v207
	v_bfe_u32 v2, v207, 2, 2
	v_lshl_add_u32 v0, v2, 5, v0
	v_bfe_u32 v2, v207, 1, 1
	v_xor_b32_e32 v2, v2, v208
	v_lshl_add_u32 v212, v2, 4, v0
	v_xor_b32_e32 v217, 32, v212
	v_xor_b32_e32 v218, 64, v212
	v_xor_b32_e32 v219, 0x60, v212
	v_lshl_add_u64 v[2:3], v[194:195], 0, s[6:7]
	s_add_i32 s6, s33, 0x4000
	s_mov_b32 s7, m0
	s_mov_b32 m0, s6
	s_nop 0
	global_load_lds_dwordx4 v[2:3], off
	s_mov_b32 m0, s7
	s_waitcnt vmcnt(3) lgkmcnt(0)
	s_barrier
	ds_read_b128 v[2:5], v212
	ds_read_b128 v[6:9], v212 offset:4096
	ds_read_b128 v[34:37], v217
	ds_read_b128 v[38:41], v217 offset:4096
	s_mov_b64 s[6:7], 0x30000
	v_lshlrev_b32_e32 v0, 1, v46
	v_and_b32_e32 v213, 32, v0
	s_mov_b32 s8, 0
	s_movk_i32 s35, 0x2000
	s_movk_i32 s36, 0x4000
	s_and_b64 vcc, exec, s[4:5]
	s_waitcnt vmcnt(3) lgkmcnt(3)
	v_mfma_f32_32x32x16_bf16 v[18:33], v[2:5], v[154:157], 0
	s_waitcnt lgkmcnt(2)
	v_mfma_f32_32x32x16_bf16 v[2:17], v[6:9], v[154:157], 0
	s_waitcnt vmcnt(2) lgkmcnt(1)
	v_mfma_f32_32x32x16_bf16 v[18:33], v[34:37], v[150:153], v[18:33]
	ds_read_b128 v[34:37], v218 offset:4096
	ds_read_b128 v[42:45], v218
	s_waitcnt lgkmcnt(2)
	v_mfma_f32_32x32x16_bf16 v[2:17], v[38:41], v[150:153], v[2:17]
	s_waitcnt vmcnt(1) lgkmcnt(0)
	v_mfma_f32_32x32x16_bf16 v[18:33], v[42:45], v[142:145], v[18:33]
	ds_read_b128 v[38:41], v219 offset:4096
	ds_read_b128 v[42:45], v219
	v_mfma_f32_32x32x16_bf16 v[2:17], v[34:37], v[142:145], v[2:17]
	v_lshlrev_b32_e32 v34, 4, v46
	v_and_b32_e32 v0, 0xc0, v34
	v_lshl_or_b32 v0, v208, 8, v0
	v_add_u32_e32 v34, 0, v213
	v_add3_u32 v214, v34, v211, v0
	s_waitcnt vmcnt(0) lgkmcnt(0)
	v_mfma_f32_32x32x16_bf16 v[18:33], v[42:45], v[134:137], v[18:33]
	v_mfma_f32_32x32x16_bf16 v[2:17], v[38:41], v[134:137], v[2:17]
	s_nop 15
	s_nop 7
	s_waitcnt vmcnt(0) lgkmcnt(0)
	s_barrier
	s_nop 10
	v_exp_f32_e32 v82, v18
	v_exp_f32_e32 v83, v19
	v_exp_f32_e32 v66, v2
	v_exp_f32_e32 v67, v3
	v_lshl_add_u64 v[2:3], v[194:195], 0, s[6:7]
	s_mov_b32 s6, m0
	s_mov_b32 m0, s33
	s_nop 0
	global_load_lds_dwordx4 v[2:3], off
	s_mov_b32 m0, s6
	v_lshl_add_u64 v[2:3], v[196:197], 0, s[76:77]
	s_add_i32 s6, s33, 0xa000
	s_mov_b32 s7, m0
	s_mov_b32 m0, s6
	s_nop 0
	global_load_lds_dwordx4 v[2:3], off
	s_mov_b32 m0, s7
	s_mov_b64 s[6:7], 0x10080
	v_lshl_add_u64 v[2:3], v[196:197], 0, s[6:7]
	s_add_i32 s6, s33, 0xc000
	s_mov_b32 s7, m0
	s_mov_b32 m0, s6
	s_nop 0
	global_load_lds_dwordx4 v[2:3], off
	s_mov_b32 m0, s7
	ds_read_b128 v[186:189], v212 offset:8192
	ds_read_b128 v[174:177], v212 offset:12288
	ds_read_b128 v[190:193], v217 offset:8192
	ds_read_b128 v[178:181], v217 offset:12288
	ds_read_b128 v[182:185], v218 offset:8192
	ds_read_b128 v[166:169], v218 offset:12288
	ds_read_b128 v[170:173], v219 offset:8192
	ds_read_b128 v[162:165], v219 offset:12288
	v_exp_f32_e32 v84, v20
	v_exp_f32_e32 v85, v21
	v_exp_f32_e32 v86, v22
	v_exp_f32_e32 v87, v23
	v_exp_f32_e32 v88, v24
	v_exp_f32_e32 v89, v25
	v_exp_f32_e32 v90, v26
	v_exp_f32_e32 v91, v27
	v_exp_f32_e32 v92, v28
	v_exp_f32_e32 v93, v29
	v_exp_f32_e32 v94, v30
	v_exp_f32_e32 v95, v31
	v_exp_f32_e32 v96, v32
	v_exp_f32_e32 v97, v33
	v_exp_f32_e32 v68, v4
	v_exp_f32_e32 v69, v5
	v_exp_f32_e32 v70, v6
	v_exp_f32_e32 v71, v7
	v_exp_f32_e32 v72, v8
	v_exp_f32_e32 v73, v9
	v_exp_f32_e32 v74, v10
	v_exp_f32_e32 v75, v11
	v_exp_f32_e32 v76, v12
	v_exp_f32_e32 v77, v13
	v_exp_f32_e32 v78, v14
	v_exp_f32_e32 v79, v15
	v_exp_f32_e32 v80, v16
	v_exp_f32_e32 v81, v17
	s_waitcnt vmcnt(3) lgkmcnt(0)
	s_barrier
; #define WAIT_BAR(N) asm volatile("s_waitcnt vmcnt(" #N ") lgkmcnt(0)\n\ts_barrier":::"memory")
;   #define RESC() do{ if(resc){ asm volatile("s_waitcnt lgkmcnt(0)":::"memory"); \
;       _Pragma("unroll") for(int d_=0;d_<2;++d_) _Pragma("unroll") for(int r=0;r<16;++r)o[d_][r]*=wsf[crow(r,hi)]; } }while(0)
;   #define ROT() do{sl_prev=sl_cur;sl_cur=sl_next;sl_next=(sl_next==(NSLOT-1)*SLOTB)?0:sl_next+SLOTB;}while(0)
;   #define RESC() do{ if(resc){ asm volatile("s_waitcnt lgkmcnt(0)":::"memory"); \
;       _Pragma("unroll") for(int d_=0;d_<4;++d_) _Pragma("unroll") for(int r=0;r<16;++r)o[d_][r]*=wsf[crow(r,hi)]; } }while(0)
;   #define ROT() do{sl_prev=sl_cur;sl_cur=sl_next;sl_next=(sl_next==(NSLOT-1)*SLOTB)?0:sl_next+SLOTB;}while(0)
; template<int THRL,bool NOMAX=false> __device__ __forceinline__ void attn_unit_v128(const bf16*Qu,int qp,const bf16*__restrict__ Kh,int kp,const bf16*__restrict__ Vh,int vp,bf16*Ou,int op,int NT,char*shm,int tid_in){
;     ...
;   int t=1;
;   for(;t+5<NT;t+=2){
;     STEP(pB0,pB1,pA0,pA1,t,true,true,true);     WAIT_BAR(3); RESC(); ROT();
	s_cbranch_vccnz .LBB0_800
	v_mov_b32_e32 v210, 0
	s_mov_b32 s9, 0
	s_mov_b32 s10, 6
	s_mov_b64 s[4:5], 0
	v_mov_b32_e32 v34, 0
	v_mov_b32_e32 v35, v210
	v_mov_b32_e32 v36, v210
	v_mov_b32_e32 v37, v210
	v_mov_b32_e32 v38, v210
	v_mov_b32_e32 v39, v210
	v_mov_b32_e32 v40, v210
	v_mov_b32_e32 v41, v210
	v_mov_b32_e32 v42, v210
	v_mov_b32_e32 v43, v210
	v_mov_b32_e32 v44, v210
	v_mov_b32_e32 v45, v210
	v_mov_b32_e32 v46, v210
	v_mov_b32_e32 v47, v210
	v_mov_b32_e32 v48, v210
	v_mov_b32_e32 v49, v210
	v_mov_b32_e32 v50, 0
	v_mov_b32_e32 v51, v210
	v_mov_b32_e32 v52, v210
	v_mov_b32_e32 v53, v210
	v_mov_b32_e32 v54, v210
	v_mov_b32_e32 v55, v210
	v_mov_b32_e32 v56, v210
	v_mov_b32_e32 v57, v210
	v_mov_b32_e32 v58, v210
	v_mov_b32_e32 v59, v210
	v_mov_b32_e32 v60, v210
	v_mov_b32_e32 v61, v210
	v_mov_b32_e32 v62, v210
	v_mov_b32_e32 v63, v210
	v_mov_b32_e32 v64, v210
	v_mov_b32_e32 v65, v210
	v_mov_b32_e32 v2, 0
	v_mov_b32_e32 v3, v210
	v_mov_b32_e32 v4, v210
	v_mov_b32_e32 v5, v210
	v_mov_b32_e32 v6, v210
	v_mov_b32_e32 v7, v210
	v_mov_b32_e32 v8, v210
	v_mov_b32_e32 v9, v210
	v_mov_b32_e32 v10, v210
	v_mov_b32_e32 v11, v210
	v_mov_b32_e32 v12, v210
	v_mov_b32_e32 v13, v210
	v_mov_b32_e32 v14, v210
	v_mov_b32_e32 v15, v210
	v_mov_b32_e32 v16, v210
	v_mov_b32_e32 v17, v210
	v_mov_b32_e32 v18, 0
	v_mov_b32_e32 v19, v210
	v_mov_b32_e32 v20, v210
	v_mov_b32_e32 v21, v210
	v_mov_b32_e32 v22, v210
	v_mov_b32_e32 v23, v210
	v_mov_b32_e32 v24, v210
	v_mov_b32_e32 v25, v210
	v_mov_b32_e32 v26, v210
	v_mov_b32_e32 v27, v210
	v_mov_b32_e32 v28, v210
	v_mov_b32_e32 v29, v210
	v_mov_b32_e32 v30, v210
	v_mov_b32_e32 v31, v210
	v_mov_b32_e32 v32, v210
	v_mov_b32_e32 v33, v210
	s_mov_b64 s[12:13], 0x40000
	s_mov_b64 s[14:15], 0x20000
	s_mov_b64 s[16:17], 0x30000
	s_mov_b64 s[18:19], 0x50000
	v_cvt_pk_bf16_f32 v158, v82, v83
	v_cvt_pk_bf16_f32 v159, v84, v85
	v_cvt_pk_bf16_f32 v160, v86, v87
	v_cvt_pk_bf16_f32 v161, v88, v89
	v_cvt_pk_bf16_f32 v146, v90, v91
	v_cvt_pk_bf16_f32 v147, v92, v93
	v_cvt_pk_bf16_f32 v148, v94, v95
	v_cvt_pk_bf16_f32 v149, v96, v97
	v_cvt_pk_bf16_f32 v138, v66, v67
	v_cvt_pk_bf16_f32 v139, v68, v69
	v_cvt_pk_bf16_f32 v140, v70, v71
	v_cvt_pk_bf16_f32 v141, v72, v73
	s_mov_b32 s100, 0x10000
	s_mov_b32 s101, 0
	v_lshl_add_u64 v[224:225], v[194:195], 0, s[4:5]
	v_lshl_add_u64 v[228:229], v[196:197], 0, s[4:5]
	v_lshl_add_u64 v[230:231], v[198:199], 0, s[4:5]
	v_lshl_add_u64 v[224:225], v[224:225], 0, s[12:13]
	v_lshl_add_u64 v[228:229], v[228:229], 0, s[14:15]
	v_lshl_add_u64 v[230:231], v[230:231], 0, s[14:15]
	s_nop 0
	v_readfirstlane_b32 s76, v224
	v_readfirstlane_b32 s77, v225
	v_readfirstlane_b32 s78, v228
	v_readfirstlane_b32 s79, v229
	v_readfirstlane_b32 s80, v230
	v_readfirstlane_b32 s81, v231
	s_nop 1
	v_subrev_u32_e32 v224, s76, v224
	v_subrev_u32_e32 v228, s78, v228
	v_subrev_u32_e32 v230, s80, v230
	v_add_u32_e32 v224, 0x100000, v224
	v_add_u32_e32 v228, 0x100000, v228
	v_add_u32_e32 v230, 0x100000, v230
	s_sub_u32 s76, s76, 0x100000
	s_subb_u32 s77, s77, 0
	s_sub_u32 s78, s78, 0x100000
	s_subb_u32 s79, s79, 0
	s_sub_u32 s80, s80, 0x100000
	s_subb_u32 s81, s81, 0
.LBB0_798:
	s_mov_b32 s8, s36
	s_mov_b32 s6, s10
	s_mov_b32 s7, s35
	v_add_f32_e32 v98, v82, v83
	v_add_f32_e32 v98, v84, v98
	v_add_f32_e32 v98, v85, v98
	v_add_f32_e32 v98, v86, v98
	v_add_f32_e32 v98, v87, v98
	v_lshl_add_u32 v201, s9, 1, v214
	s_waitcnt lgkmcnt(7)
	v_mfma_f32_32x32x16_bf16 v[114:129], v[186:189], v[154:157], 0
	s_nop 0
	v_add_f32_e32 v82, v88, v98
	v_add_f32_e32 v82, v89, v82
	v_add_f32_e32 v82, v90, v82
	v_add_f32_e32 v82, v91, v82
	s_waitcnt lgkmcnt(6)
	v_mfma_f32_32x32x16_bf16 v[98:113], v[174:177], v[154:157], 0
	v_add_f32_e32 v82, v92, v82
	v_add_f32_e32 v82, v93, v82
	v_add_f32_e32 v82, v94, v82
	v_add_f32_e32 v86, v95, v82
	s_waitcnt lgkmcnt(5)
	v_mfma_f32_32x32x16_bf16 v[114:129], v[190:193], v[150:153], v[114:129]
	ds_read_b64_tr_b16 v[82:83], v201 offset:24576
	ds_read_b64_tr_b16 v[84:85], v201 offset:25088
	v_add_f32_e32 v86, v96, v86
	v_add_f32_e32 v86, v97, v86
	v_add_f32_e32 v86, v66, v86
	v_add_f32_e32 v90, v67, v86
	s_waitcnt lgkmcnt(6)
	v_mfma_f32_32x32x16_bf16 v[98:113], v[178:181], v[150:153], v[98:113]
	ds_read_b64_tr_b16 v[86:87], v201 offset:28672
	ds_read_b64_tr_b16 v[88:89], v201 offset:29184
	v_add_f32_e32 v90, v68, v90
	v_add_f32_e32 v90, v69, v90
	v_add_f32_e32 v90, v70, v90
	v_add_f32_e32 v90, v71, v90
	s_waitcnt lgkmcnt(7)
	v_mfma_f32_32x32x16_bf16 v[114:129], v[182:185], v[142:145], v[114:129]
	ds_read_b64_tr_b16 v[66:67], v201 offset:32768
	ds_read_b64_tr_b16 v[68:69], v201 offset:33280
	v_add_f32_e32 v90, v72, v90
	v_add_f32_e32 v90, v73, v90
	v_add_f32_e32 v90, v74, v90
	v_add_f32_e32 v90, v75, v90
	s_waitcnt lgkmcnt(8)
	v_mfma_f32_32x32x16_bf16 v[98:113], v[166:169], v[142:145], v[98:113]
	ds_read_b64_tr_b16 v[70:71], v201 offset:36864
	ds_read_b64_tr_b16 v[72:73], v201 offset:37376
	v_add_f32_e32 v90, v76, v90
	v_add_f32_e32 v90, v77, v90
	v_add_f32_e32 v90, v78, v90
	v_add_f32_e32 v90, v79, v90
	v_cvt_pk_bf16_f32 v130, v74, v75
	v_cvt_pk_bf16_f32 v131, v76, v77
	s_waitcnt lgkmcnt(9)
	v_mfma_f32_32x32x16_bf16 v[114:129], v[170:173], v[134:137], v[114:129]
	ds_read_b64_tr_b16 v[74:75], v201 offset:25600
	ds_read_b64_tr_b16 v[76:77], v201 offset:26112
	v_add_f32_e32 v90, v80, v90
	v_add_f32_e32 v90, v81, v90
	v_add_f32_e32 v200, 0, v90
	v_cvt_pk_bf16_f32 v132, v78, v79
	v_cvt_pk_bf16_f32 v133, v80, v81
	s_waitcnt lgkmcnt(10)
	v_mfma_f32_32x32x16_bf16 v[98:113], v[162:165], v[134:137], v[98:113]
	s_add_i32 s9, s35, s33
	s_mov_b32 m0, s9
	s_nop 0
	global_load_lds_dwordx4 v224, s[76:77]
	s_lshl_b32 s9, s36, 1
	s_add_i32 s9, s9, s34
	s_mov_b32 m0, s9
	s_nop 0
	global_load_lds_dwordx4 v228, s[78:79]
	s_addk_i32 s9, 0x2000
	s_mov_b32 m0, s9
	s_nop 0
	global_load_lds_dwordx4 v230, s[80:81]
	s_waitcnt lgkmcnt(8)
	v_mfma_f32_32x32x16_bf16 v[34:49], v[158:161], v[82:85], v[34:49]
	v_exp_f32_e32 v114, v114
	v_exp_f32_e32 v115, v115
	ds_read_b64_tr_b16 v[78:79], v201 offset:29696
	ds_read_b64_tr_b16 v[80:81], v201 offset:30208
	s_waitcnt lgkmcnt(8)
	v_mfma_f32_32x32x16_bf16 v[50:65], v[158:161], v[86:89], v[50:65]
	v_exp_f32_e32 v116, v116
	v_exp_f32_e32 v117, v117
	s_add_u32 s76, s76, 0x10000
	s_addc_u32 s77, s77, 0
	ds_read_b64_tr_b16 v[82:83], v201 offset:33792
	ds_read_b64_tr_b16 v[84:85], v201 offset:34304
	s_waitcnt lgkmcnt(8)
	v_mfma_f32_32x32x16_bf16 v[2:17], v[158:161], v[66:69], v[2:17]
	v_exp_f32_e32 v118, v118
	v_exp_f32_e32 v119, v119
	s_add_u32 s78, s78, 0x10000
	s_addc_u32 s79, s79, 0
	ds_read_b64_tr_b16 v[86:87], v201 offset:37888
	ds_read_b64_tr_b16 v[88:89], v201 offset:38400
	s_waitcnt lgkmcnt(8)
	v_mfma_f32_32x32x16_bf16 v[18:33], v[158:161], v[70:73], v[18:33]
	v_exp_f32_e32 v120, v120
	v_exp_f32_e32 v121, v121
	s_add_u32 s80, s80, 0x10000
	s_addc_u32 s81, s81, 0
	ds_read_b64_tr_b16 v[70:71], v201 offset:26624
	ds_read_b64_tr_b16 v[72:73], v201 offset:27136
	v_add_u32_e32 v94, s8, v212
	v_add_u32_e32 v220, s8, v217
	v_add_u32_e32 v221, s8, v218
	v_add_u32_e32 v222, s8, v219
	ds_read_b128 v[90:93], v94
	ds_read_b128 v[66:69], v94 offset:4096
	s_waitcnt lgkmcnt(10)
	v_mfma_f32_32x32x16_bf16 v[34:49], v[146:149], v[74:77], v[34:49]
	v_exp_f32_e32 v122, v122
	v_exp_f32_e32 v123, v123
	v_cvt_pk_bf16_f32 v158, v114, v115
	ds_read_b64_tr_b16 v[74:75], v201 offset:30720
	ds_read_b64_tr_b16 v[76:77], v201 offset:31232
	s_waitcnt lgkmcnt(10)
	v_mfma_f32_32x32x16_bf16 v[50:65], v[146:149], v[78:81], v[50:65]
	v_exp_f32_e32 v124, v124
	v_exp_f32_e32 v125, v125
	v_cvt_pk_bf16_f32 v159, v116, v117
	ds_read_b64_tr_b16 v[78:79], v201 offset:34816
	ds_read_b64_tr_b16 v[80:81], v201 offset:35328
	s_waitcnt lgkmcnt(10)
	v_mfma_f32_32x32x16_bf16 v[2:17], v[146:149], v[82:85], v[2:17]
	v_exp_f32_e32 v126, v126
	v_exp_f32_e32 v127, v127
	v_cvt_pk_bf16_f32 v160, v118, v119
	ds_read_b64_tr_b16 v[82:83], v201 offset:38912
	ds_read_b64_tr_b16 v[84:85], v201 offset:39424
	ds_read_b128 v[168:171], v220
	ds_read_b128 v[172:175], v220 offset:4096
	s_waitcnt lgkmcnt(12)
	v_mfma_f32_32x32x16_bf16 v[18:33], v[146:149], v[86:89], v[18:33]
	v_exp_f32_e32 v128, v128
	v_exp_f32_e32 v129, v129
	v_cvt_pk_bf16_f32 v161, v120, v121
	ds_read_b64_tr_b16 v[86:87], v201 offset:27648
	ds_read_b64_tr_b16 v[88:89], v201 offset:28160
	s_waitcnt lgkmcnt(12)
	v_mfma_f32_32x32x16_bf16 v[34:49], v[138:141], v[70:73], v[34:49]
	v_exp_f32_e32 v98, v98
	v_exp_f32_e32 v99, v99
	v_cvt_pk_bf16_f32 v146, v122, v123
	ds_read_b64_tr_b16 v[70:71], v201 offset:31744
	ds_read_b64_tr_b16 v[72:73], v201 offset:32256
	s_waitcnt lgkmcnt(10)
	v_mfma_f32_32x32x16_bf16 v[50:65], v[138:141], v[74:77], v[50:65]
	v_exp_f32_e32 v100, v100
	v_exp_f32_e32 v101, v101
	v_cvt_pk_bf16_f32 v147, v124, v125
	ds_read_b64_tr_b16 v[74:75], v201 offset:35840
	ds_read_b64_tr_b16 v[76:77], v201 offset:36352
	ds_read_b128 v[176:179], v221
	ds_read_b128 v[180:183], v221 offset:4096
	s_waitcnt lgkmcnt(12)
	v_mfma_f32_32x32x16_bf16 v[2:17], v[138:141], v[78:81], v[2:17]
	v_exp_f32_e32 v102, v102
	v_exp_f32_e32 v103, v103
	v_cvt_pk_bf16_f32 v148, v126, v127
	ds_read_b64_tr_b16 v[78:79], v201 offset:39936
	ds_read_b64_tr_b16 v[80:81], v201 offset:40448
	s_waitcnt lgkmcnt(12)
	v_mfma_f32_32x32x16_bf16 v[18:33], v[138:141], v[82:85], v[18:33]
	v_exp_f32_e32 v104, v104
	v_exp_f32_e32 v105, v105
	v_cvt_pk_bf16_f32 v149, v128, v129
	s_waitcnt lgkmcnt(8)
	v_mfma_f32_32x32x16_bf16 v[34:49], v[130:133], v[86:89], v[34:49]
	v_exp_f32_e32 v106, v106
	v_exp_f32_e32 v107, v107
	v_cvt_pk_bf16_f32 v138, v98, v99
	ds_read_b128 v[184:187], v222
	ds_read_b128 v[188:191], v222 offset:4096
	s_waitcnt lgkmcnt(8)
	v_mfma_f32_32x32x16_bf16 v[50:65], v[130:133], v[70:73], v[50:65]
	v_exp_f32_e32 v108, v108
	v_exp_f32_e32 v109, v109
	v_cvt_pk_bf16_f32 v139, v100, v101
	s_waitcnt lgkmcnt(6)
	v_mfma_f32_32x32x16_bf16 v[2:17], v[130:133], v[74:77], v[2:17]
	v_exp_f32_e32 v110, v110
	v_exp_f32_e32 v111, v111
	v_cvt_pk_bf16_f32 v140, v102, v103
	s_waitcnt lgkmcnt(2)
	v_mfma_f32_32x32x16_bf16 v[18:33], v[130:133], v[78:81], v[18:33]
	v_exp_f32_e32 v112, v112
	v_exp_f32_e32 v113, v113
	v_cvt_pk_bf16_f32 v141, v104, v105
	s_waitcnt vmcnt(3) lgkmcnt(0)
	s_barrier
	s_add_i32 s9, s36, 0x2000
	s_cmpk_lg_i32 s36, 0x4000
	s_cselect_b32 s35, s9, 0
	v_mfma_f32_32x32x16_bf16 v[82:97], v[90:93], v[154:157], 0
	v_add_f32_e32 v70, v114, v115
	v_add_f32_e32 v70, v116, v70
	v_add_f32_e32 v70, v117, v70
	v_add_f32_e32 v70, v118, v70
	v_add_f32_e32 v70, v119, v70
	v_lshl_add_u32 v201, s7, 1, v214
	s_nop 0
	v_add_f32_e32 v70, v120, v70
	v_add_f32_e32 v70, v121, v70
	v_add_f32_e32 v70, v122, v70
	v_add_f32_e32 v114, v123, v70
	v_mfma_f32_32x32x16_bf16 v[66:81], v[66:69], v[154:157], 0
	v_mfma_f32_32x32x16_bf16 v[82:97], v[168:171], v[150:153], v[82:97]
	v_add_f32_e32 v114, v124, v114
	v_add_f32_e32 v114, v125, v114
	v_add_f32_e32 v114, v126, v114
	v_add_f32_e32 v118, v127, v114
	ds_read_b64_tr_b16 v[114:115], v201 offset:24576
	ds_read_b64_tr_b16 v[116:117], v201 offset:25088
	v_mfma_f32_32x32x16_bf16 v[66:81], v[172:175], v[150:153], v[66:81]
	v_add_f32_e32 v118, v128, v118
	v_add_f32_e32 v118, v129, v118
	v_add_f32_e32 v118, v98, v118
	v_add_f32_e32 v122, v99, v118
	ds_read_b64_tr_b16 v[118:119], v201 offset:28672
	ds_read_b64_tr_b16 v[120:121], v201 offset:29184
	v_mfma_f32_32x32x16_bf16 v[82:97], v[176:179], v[142:145], v[82:97]
	v_add_f32_e32 v122, v100, v122
	v_add_f32_e32 v122, v101, v122
	v_add_f32_e32 v122, v102, v122
	v_add_f32_e32 v122, v103, v122
	ds_read_b64_tr_b16 v[98:99], v201 offset:32768
	ds_read_b64_tr_b16 v[100:101], v201 offset:33280
	v_mfma_f32_32x32x16_bf16 v[66:81], v[180:183], v[142:145], v[66:81]
	v_add_f32_e32 v122, v104, v122
	v_add_f32_e32 v122, v105, v122
	v_add_f32_e32 v122, v106, v122
	v_add_f32_e32 v122, v107, v122
	ds_read_b64_tr_b16 v[102:103], v201 offset:36864
	ds_read_b64_tr_b16 v[104:105], v201 offset:37376
	s_waitcnt lgkmcnt(9)
	v_mfma_f32_32x32x16_bf16 v[82:97], v[184:187], v[134:137], v[82:97]
	v_add_f32_e32 v122, v108, v122
	v_add_f32_e32 v122, v109, v122
	v_add_f32_e32 v122, v110, v122
	v_add_f32_e32 v122, v111, v122
	v_cvt_pk_bf16_f32 v130, v106, v107
	v_cvt_pk_bf16_f32 v131, v108, v109
	ds_read_b64_tr_b16 v[106:107], v201 offset:25600
	ds_read_b64_tr_b16 v[108:109], v201 offset:26112
	s_waitcnt lgkmcnt(10)
	v_mfma_f32_32x32x16_bf16 v[66:81], v[188:191], v[134:137], v[66:81]
	v_add_f32_e32 v122, v112, v122
	v_add_f32_e32 v122, v113, v122
	v_add_f32_e32 v122, 0, v122
	v_cvt_pk_bf16_f32 v132, v110, v111
	v_cvt_pk_bf16_f32 v133, v112, v113
	s_add_i32 s7, s36, s33
	s_mov_b32 m0, s7
	s_nop 0
	global_load_lds_dwordx4 v224, s[76:77]
	s_lshl_b32 s7, s35, 1
	s_add_i32 s7, s7, s34
	s_mov_b32 m0, s7
	s_nop 0
	global_load_lds_dwordx4 v228, s[78:79]
	s_addk_i32 s7, 0x2000
	s_mov_b32 m0, s7
	s_nop 0
	global_load_lds_dwordx4 v230, s[80:81]
	s_waitcnt lgkmcnt(8)
	v_mfma_f32_32x32x16_bf16 v[34:49], v[158:161], v[114:117], v[34:49]
	v_exp_f32_e32 v82, v82
	v_exp_f32_e32 v83, v83
	ds_read_b64_tr_b16 v[110:111], v201 offset:29696
	ds_read_b64_tr_b16 v[112:113], v201 offset:30208
	s_waitcnt lgkmcnt(8)
	v_mfma_f32_32x32x16_bf16 v[50:65], v[158:161], v[118:121], v[50:65]
	v_exp_f32_e32 v84, v84
	v_exp_f32_e32 v85, v85
	s_add_u32 s76, s76, 0x10000
	s_addc_u32 s77, s77, 0
	ds_read_b64_tr_b16 v[114:115], v201 offset:33792
	ds_read_b64_tr_b16 v[116:117], v201 offset:34304
	s_waitcnt lgkmcnt(8)
	v_mfma_f32_32x32x16_bf16 v[2:17], v[158:161], v[98:101], v[2:17]
	v_exp_f32_e32 v86, v86
	v_exp_f32_e32 v87, v87
	s_add_u32 s78, s78, 0x10000
	s_addc_u32 s79, s79, 0
	ds_read_b64_tr_b16 v[98:99], v201 offset:37888
	ds_read_b64_tr_b16 v[100:101], v201 offset:38400
	s_waitcnt lgkmcnt(8)
; #define WAIT_BAR(N) asm volatile("s_waitcnt vmcnt(" #N ") lgkmcnt(0)\n\ts_barrier":::"memory")
;   #define RESC() do{ if(resc){ asm volatile("s_waitcnt lgkmcnt(0)":::"memory"); \
;       _Pragma("unroll") for(int d_=0;d_<2;++d_) _Pragma("unroll") for(int r=0;r<16;++r)o[d_][r]*=wsf[crow(r,hi)]; } }while(0)
;   #define ROT() do{sl_prev=sl_cur;sl_cur=sl_next;sl_next=(sl_next==(NSLOT-1)*SLOTB)?0:sl_next+SLOTB;}while(0)
;   #define RESC() do{ if(resc){ asm volatile("s_waitcnt lgkmcnt(0)":::"memory"); \
;       _Pragma("unroll") for(int d_=0;d_<4;++d_) _Pragma("unroll") for(int r=0;r<16;++r)o[d_][r]*=wsf[crow(r,hi)]; } }while(0)
;   #define ROT() do{sl_prev=sl_cur;sl_cur=sl_next;sl_next=(sl_next==(NSLOT-1)*SLOTB)?0:sl_next+SLOTB;}while(0)
; template<int THRL,bool NOMAX=false> __device__ __forceinline__ void attn_unit_v128(const bf16*Qu,int qp,const bf16*__restrict__ Kh,int kp,const bf16*__restrict__ Vh,int vp,bf16*Ou,int op,int NT,char*shm,int tid_in){
;     ...
;   int t=1;
;   for(;t+5<NT;t+=2){
;     STEP(pB0,pB1,pA0,pA1,t,true,true,true);     WAIT_BAR(3); RESC(); ROT();
;     STEP(pA0,pA1,pB0,pB1,t+1,true,true,true);   WAIT_BAR(3); RESC(); ROT();
	v_mfma_f32_32x32x16_bf16 v[18:33], v[158:161], v[102:105], v[18:33]
	v_exp_f32_e32 v88, v88
	v_exp_f32_e32 v89, v89
	s_add_u32 s80, s80, 0x10000
	s_addc_u32 s81, s81, 0
	ds_read_b64_tr_b16 v[102:103], v201 offset:26624
	ds_read_b64_tr_b16 v[104:105], v201 offset:27136
	v_add_u32_e32 v118, s35, v212
	v_add_u32_e32 v220, s35, v217
	v_add_u32_e32 v221, s35, v218
	v_add_u32_e32 v222, s35, v219
	ds_read_b128 v[186:189], v118
	ds_read_b128 v[174:177], v118 offset:4096
	s_waitcnt lgkmcnt(10)
	v_mfma_f32_32x32x16_bf16 v[34:49], v[146:149], v[106:109], v[34:49]
	v_exp_f32_e32 v90, v90
	v_exp_f32_e32 v91, v91
	v_cvt_pk_bf16_f32 v158, v82, v83
	ds_read_b64_tr_b16 v[106:107], v201 offset:30720
	ds_read_b64_tr_b16 v[108:109], v201 offset:31232
	s_waitcnt lgkmcnt(10)
	v_mfma_f32_32x32x16_bf16 v[50:65], v[146:149], v[110:113], v[50:65]
	v_exp_f32_e32 v92, v92
	v_exp_f32_e32 v93, v93
	v_cvt_pk_bf16_f32 v159, v84, v85
	ds_read_b64_tr_b16 v[110:111], v201 offset:34816
	ds_read_b64_tr_b16 v[112:113], v201 offset:35328
	s_waitcnt lgkmcnt(10)
	v_mfma_f32_32x32x16_bf16 v[2:17], v[146:149], v[114:117], v[2:17]
	v_exp_f32_e32 v94, v94
	v_exp_f32_e32 v95, v95
	v_cvt_pk_bf16_f32 v160, v86, v87
	ds_read_b64_tr_b16 v[114:115], v201 offset:38912
	ds_read_b64_tr_b16 v[116:117], v201 offset:39424
	ds_read_b128 v[190:193], v220
	ds_read_b128 v[178:181], v220 offset:4096
	s_waitcnt lgkmcnt(12)
	v_mfma_f32_32x32x16_bf16 v[18:33], v[146:149], v[98:101], v[18:33]
	v_exp_f32_e32 v96, v96
	v_exp_f32_e32 v97, v97
	v_cvt_pk_bf16_f32 v161, v88, v89
	ds_read_b64_tr_b16 v[98:99], v201 offset:27648
	ds_read_b64_tr_b16 v[100:101], v201 offset:28160
	s_waitcnt lgkmcnt(12)
	v_mfma_f32_32x32x16_bf16 v[34:49], v[138:141], v[102:105], v[34:49]
	v_exp_f32_e32 v66, v66
	v_exp_f32_e32 v67, v67
	v_cvt_pk_bf16_f32 v146, v90, v91
	ds_read_b64_tr_b16 v[102:103], v201 offset:31744
	ds_read_b64_tr_b16 v[104:105], v201 offset:32256
	s_waitcnt lgkmcnt(10)
	v_mfma_f32_32x32x16_bf16 v[50:65], v[138:141], v[106:109], v[50:65]
	v_exp_f32_e32 v68, v68
	v_exp_f32_e32 v69, v69
	v_cvt_pk_bf16_f32 v147, v92, v93
	ds_read_b64_tr_b16 v[106:107], v201 offset:35840
	ds_read_b64_tr_b16 v[108:109], v201 offset:36352
	ds_read_b128 v[182:185], v221
	ds_read_b128 v[166:169], v221 offset:4096
	s_waitcnt lgkmcnt(12)
	v_mfma_f32_32x32x16_bf16 v[2:17], v[138:141], v[110:113], v[2:17]
	v_exp_f32_e32 v70, v70
	v_exp_f32_e32 v71, v71
	v_cvt_pk_bf16_f32 v148, v94, v95
	ds_read_b64_tr_b16 v[110:111], v201 offset:39936
	ds_read_b64_tr_b16 v[112:113], v201 offset:40448
	s_waitcnt lgkmcnt(12)
	v_mfma_f32_32x32x16_bf16 v[18:33], v[138:141], v[114:117], v[18:33]
	v_exp_f32_e32 v72, v72
	v_exp_f32_e32 v73, v73
	v_cvt_pk_bf16_f32 v149, v96, v97
	s_waitcnt lgkmcnt(8)
	v_mfma_f32_32x32x16_bf16 v[34:49], v[130:133], v[98:101], v[34:49]
	v_exp_f32_e32 v74, v74
	v_exp_f32_e32 v75, v75
	v_cvt_pk_bf16_f32 v138, v66, v67
	ds_read_b128 v[170:173], v222
	ds_read_b128 v[162:165], v222 offset:4096
	s_waitcnt lgkmcnt(8)
	v_mfma_f32_32x32x16_bf16 v[50:65], v[130:133], v[102:105], v[50:65]
	v_exp_f32_e32 v76, v76
	v_exp_f32_e32 v77, v77
	v_cvt_pk_bf16_f32 v139, v68, v69
	s_waitcnt lgkmcnt(6)
	v_mfma_f32_32x32x16_bf16 v[2:17], v[130:133], v[106:109], v[2:17]
	v_exp_f32_e32 v78, v78
	v_exp_f32_e32 v79, v79
	v_cvt_pk_bf16_f32 v140, v70, v71
	s_waitcnt lgkmcnt(2)
	v_mfma_f32_32x32x16_bf16 v[18:33], v[130:133], v[110:113], v[18:33]
	v_exp_f32_e32 v80, v80
	v_exp_f32_e32 v81, v81
	v_cvt_pk_bf16_f32 v141, v72, v73
	s_add_i32 s7, s35, 0x2000
	s_cmpk_lg_i32 s35, 0x4000
	s_mov_b32 s9, s36
	s_cselect_b32 s36, s7, 0
	s_add_i32 s10, s6, 2
	s_waitcnt vmcnt(3) lgkmcnt(0)
	s_barrier
	s_add_u32 s4, s4, 0x20000
	v_add_f32_e32 v98, v210, v200
	s_addc_u32 s5, s5, 0
	s_cmp_ge_u32 s10, s75
	v_add_f32_e32 v210, v98, v122
	s_cbranch_scc0 .LBB0_798
	s_add_i32 s86, s6, -3
	s_add_i32 s4, s86, 1
	s_cmp_ge_u32 s4, s75
	s_mov_b64 s[4:5], -1
	s_cbranch_scc0 .LBB0_802
	s_branch .LBB0_801

;   #define DMA_K(t,slot) glds16(ksrc+(long)(t)*KVBLK*kp,(unsigned)__builtin_amdgcn_readfirstlane(kdst+(slot)))
;   #define DMA_V(t,slot) glds16(vsrc+(long)(t)*KVBLK*vp,(unsigned)__builtin_amdgcn_readfirstlane(vdst+(slot)))
;   #define DMA_K(t,slot) glds16(ksrc+(long)(t)*KVBLK*kp,(unsigned)__builtin_amdgcn_readfirstlane(kdst+(slot)))
;   #define DMA_V(t,slot) glds16(vsrc+(long)(t)*KVBLK*vp,(unsigned)__builtin_amdgcn_readfirstlane(vdst+(slot)))
;   #define MF(k,q,c) __builtin_amdgcn_mfma_f32_32x32x16_bf16(k,q,c,0,0,0)
;   #define DMA_K(t,slot) glds16(ksrc+(long)(t)*KVBLK*kp,(unsigned)__builtin_amdgcn_readfirstlane(kdst+(slot)))
; __device__ __forceinline__ void attn_unit2(const bf16*Qu,int qp,const bf16*__restrict__ Kh,int kp,const bf16*__restrict__ Vh,int vp,bf16*Ou,int op,int NT,char*shm,int tid_in){
;   int tid_=tid_in; asm volatile("":"+v"(tid_));
;   const int tid=tid_,lane=tid&63,r32=lane&31,hi=lane>>5; const int wid=__builtin_amdgcn_readfirstlane(tid>>6);
;   const bf16*Qw=Qu+(long)(wid*64)*qp;
;   const unsigned lds0=(unsigned)(uintptr_t)shm;
;   float*wsf=(float*)(shm+U2_WS)+wid*64;
;   const bf16*ksrc=Kh+(long)lane*kp+wid*8;
;   const bf16*vsrc=Vh+(long)(16*(wid&3)+(lane>>2))*vp+(wid>>2)*32+(lane&3)*8;
;   const unsigned kdst=lds0+U2_K+wid*1024, vdst=lds0+U2_V+wid*1024;
;     ...
;   const lds_cptr shm3=(lds_cptr)shm; const lds_cptr kp0=shm3+U2_K+hi*1024+r32*16; const lds_cptr vp0=shm3+U2_V+((lane>>4)&1)*32+(lane&3)*8+(4*hi+((lane&15)>>2))*64;
;   DMA_K(0,0);DMA_V(0,0);DMA_K(1,SLOTB);DMA_V(1,SLOTB);DMA_K(2,2*SLOTB);DMA_V(2,2*SLOTB);
;   bf16x8 qa[4],qb[4];
;   #pragma unroll
;   for(int d0=0;d0<4;++d0){qa[d0]=*reinterpret_cast<const bf16x8*>(&Qw[(long)r32*qp+d0*16+hi*8]);qb[d0]=*reinterpret_cast<const bf16x8*>(&Qw[(long)(32+r32)*qp+d0*16+hi*8]);}
;   float la=0.f,lb=0.f; f32x16 oa[2],ob[2]; oa[0]=f32x16{};oa[1]=f32x16{};ob[0]=f32x16{};ob[1]=f32x16{};
;   asm volatile("s_waitcnt vmcnt(0) lgkmcnt(0)\n\ts_barrier":::"memory");
;   int sl_cur=0,sl_n1=SLOTB,sl_n3=3*SLOTB;
;   bf16x8 kf[8]; kload8(kf,kp0);
;   f32x16 a0,a1,b0,b1; const f32x16 z16=f32x16{}; u32x4 pa[4],pb[4];
;     ...
;   #pragma unroll
;   for(int d0=0;d0<4;++d0){ a0=MF(kf[2*d0],qa[d0],d0==0?z16:a0); a1=MF(kf[2*d0+1],qa[d0],d0==0?z16:a1); }
.LBB0_894:
	s_and_b64 vcc, exec, s[2:3]
	s_cbranch_vccz .LBB0_923
	s_ashr_i32 s2, s72, 7
	s_ashr_i32 s3, s2, 31
	s_lshl_b32 s4, s72, 18
	s_and_b32 s6, s4, 0x3c0000
	s_lshl_b64 s[4:5], s[2:3], 22
	s_or_b32 s4, s4, s6
	s_bfe_u32 s8, s72, 0x30004
	s_lshl_b64 s[6:7], s[4:5], 1
	s_add_u32 s3, s43, s6
	s_addc_u32 s4, s44, s7
	s_lshl_b32 s10, s8, 6
	s_lshl_b32 s5, s8, 7
	s_add_u32 s14, s3, s5
	s_addc_u32 s15, s4, 0
	s_mul_hi_i32 s3, s2, 0x210000
	s_mul_i32 s2, s2, 0x210000
	s_add_u32 s4, s52, s2
	s_addc_u32 s5, s53, s3
	s_and_b32 s8, s72, 64
	s_lshl_b32 s11, s8, 1
	s_add_u32 s8, s4, s11
	s_addc_u32 s9, s5, 0
	s_add_u32 s2, s45, s2
	s_addc_u32 s3, s46, s3
	s_add_u32 s12, s2, s11
	v_readlane_b32 s2, v253, 6
	v_mbcnt_lo_u32_b32 v0, -1, 0
	v_mbcnt_hi_u32_b32 v0, -1, v0
	s_addc_u32 s13, s3, 0
	v_mov_b32_e32 v239, 0x260
	s_waitcnt vmcnt(9)
	v_or_b32_e32 v42, s2, v0
	s_nop 0
	v_readfirstlane_b32 s16, v42
	s_and_b32 s2, s16, 0xffffffc0
	s_ashr_i32 s3, s2, 31
	v_and_b32_e32 v249, 63, v42
	s_ashr_i32 s11, s16, 6
	s_lshl_b64 s[4:5], s[2:3], 10
	s_add_u32 s14, s14, s4
	v_lshlrev_b32_e32 v0, 8, v249
	s_addc_u32 s15, s15, s5
	v_lshl_add_u64 v[2:3], s[8:9], 0, v[0:1]
	s_lshl_b32 s8, s11, 3
	s_lshl_b32 s3, s11, 4
	v_bfe_u32 v0, v42, 2, 4
	s_ashr_i32 s9, s8, 31
	v_and_or_b32 v0, s3, 48, v0
	s_ashr_i32 s3, s16, 3
	v_lshl_add_u64 v[98:99], s[8:9], 1, v[2:3]
	s_and_b32 s8, s3, 0xffffffe0
	v_lshlrev_b32_e32 v0, 8, v0
	s_ashr_i32 s9, s8, 31
	s_lshl_b32 s3, s11, 10
	v_lshl_add_u64 v[2:3], s[12:13], 0, v[0:1]
	v_lshlrev_b32_e32 v248, 3, v42
	s_cmp_lg_u32 0, -1
	v_lshl_add_u64 v[2:3], s[8:9], 1, v[2:3]
	v_and_b32_e32 v43, 24, v248
	s_cselect_b32 s8, 0, 0
	v_lshlrev_b32_e32 v0, 1, v43
	s_add_i32 s3, s3, s8
	s_mov_b32 s8, m0
	s_mov_b32 m0, s3
	s_nop 0
	global_load_lds_dwordx4 v[98:99], off
	s_mov_b32 m0, s8
	v_lshl_add_u64 v[100:101], v[2:3], 0, v[0:1]
	s_add_i32 s12, s3, 0x8000
	s_mov_b32 s8, m0
	s_mov_b32 m0, s12
	s_nop 0
	global_load_lds_dwordx4 v[100:101], off
	s_mov_b32 m0, s8
	s_mov_b64 s[16:17], 0x4000
	v_lshl_add_u64 v[2:3], v[98:99], 0, s[16:17]
	s_add_i32 s8, s3, 0x2000
	s_mov_b32 s9, m0
	s_mov_b32 m0, s8
	s_nop 0
	global_load_lds_dwordx4 v[2:3], off
	s_mov_b32 m0, s9
	v_and_b32_e32 v251, 31, v42
	v_lshl_add_u64 v[2:3], v[100:101], 0, s[16:17]
	s_add_i32 s8, s3, 0xa000
	s_mov_b32 s9, m0
	s_mov_b32 m0, s8
	s_nop 0
	global_load_lds_dwordx4 v[2:3], off
	s_mov_b32 m0, s9
	s_mov_b64 s[16:17], 0x8000
	v_bfe_u32 v238, v42, 5, 1
	v_lshl_add_u64 v[2:3], v[98:99], 0, s[16:17]
	s_add_i32 s8, s3, 0x4000
	s_mov_b32 s9, m0
	s_mov_b32 m0, s8
	s_nop 0
	global_load_lds_dwordx4 v[2:3], off
	s_mov_b32 m0, s9
	v_lshlrev_b32_e32 v0, 10, v251
	v_lshl_add_u64 v[2:3], v[100:101], 0, s[16:17]
	s_add_i32 s8, s3, 0xc000
	s_mov_b32 s9, m0
	s_mov_b32 m0, s8
	s_nop 0
	global_load_lds_dwordx4 v[2:3], off
	s_mov_b32 m0, s9
	v_lshl_or_b32 v0, v238, 4, v0
	global_load_dwordx4 v[170:173], v0, s[14:15]
	global_load_dwordx4 v[174:177], v0, s[14:15] offset:32
	global_load_dwordx4 v[178:181], v0, s[14:15] offset:64
	global_load_dwordx4 v[182:185], v0, s[14:15] offset:96
	v_lshlrev_b32_e32 v2, 10, v238
	v_lshlrev_b32_e32 v3, 4, v251
	v_add3_u32 v241, 0, v2, v3
	v_lshl_add_u64 v[2:3], s[14:15], 0, v[0:1]
	v_add_co_u32_e32 v2, vcc, s33, v2
	v_lshlrev_b32_e32 v0, 1, v42
	s_nop 0
	v_addc_co_u32_e32 v3, vcc, 0, v3, vcc
	global_load_dwordx4 v[150:153], v[2:3], off
	global_load_dwordx4 v[146:149], v[2:3], off offset:32
	global_load_dwordx4 v[142:145], v[2:3], off offset:64
	global_load_dwordx4 v[130:133], v[2:3], off offset:96
	s_waitcnt vmcnt(0) lgkmcnt(0)
	s_barrier
	ds_read_b128 v[34:37], v241
	ds_read_b128 v[38:41], v241 offset:512
	ds_read_b128 v[66:69], v241 offset:2048
	ds_read_b128 v[70:73], v241 offset:2560
	ds_read_b128 v[74:77], v241 offset:4096
	ds_read_b128 v[78:81], v241 offset:4608
	ds_read_b128 v[82:85], v241 offset:6144
	ds_read_b128 v[86:89], v241 offset:6656
	v_and_b32_e32 v0, 32, v0
	v_add3_u32 v0, 0, v0, v43
	s_mov_b64 s[8:9], 0xc000
	v_lshlrev_b32_e32 v42, 4, v42
	v_lshlrev_b32_e32 v44, 8, v238
	v_and_b32_e32 v42, 0xc0, v42
	s_mov_b32 s13, 1
	s_mov_b32 s15, 0
	s_movk_i32 s14, 0x2000
	s_movk_i32 s16, 0x4000
	v_add3_u32 v0, v0, v44, v42
	s_waitcnt vmcnt(7) lgkmcnt(7)
	v_mfma_f32_32x32x16_bf16 v[2:17], v[34:37], v[170:173], 0
	s_waitcnt lgkmcnt(6)
	v_mfma_f32_32x32x16_bf16 v[18:33], v[38:41], v[170:173], 0
	s_waitcnt vmcnt(6) lgkmcnt(5)
	v_mfma_f32_32x32x16_bf16 v[2:17], v[66:69], v[174:177], v[2:17]
	s_waitcnt lgkmcnt(4)
	v_mfma_f32_32x32x16_bf16 v[18:33], v[70:73], v[174:177], v[18:33]
	s_waitcnt vmcnt(5) lgkmcnt(3)
	v_mfma_f32_32x32x16_bf16 v[2:17], v[74:77], v[178:181], v[2:17]
	s_waitcnt lgkmcnt(2)
	v_mfma_f32_32x32x16_bf16 v[18:33], v[78:81], v[178:181], v[18:33]
	s_waitcnt vmcnt(4) lgkmcnt(1)
	v_mfma_f32_32x32x16_bf16 v[2:17], v[82:85], v[182:185], v[2:17]
	s_waitcnt lgkmcnt(0)
;   #define DMA_K(t,slot) glds16(ksrc+(long)(t)*KVBLK*kp,(unsigned)__builtin_amdgcn_readfirstlane(kdst+(slot)))
;   #define DMA_V(t,slot) glds16(vsrc+(long)(t)*KVBLK*vp,(unsigned)__builtin_amdgcn_readfirstlane(vdst+(slot)))
;   #define DMA_K(t,slot) glds16(ksrc+(long)(t)*KVBLK*kp,(unsigned)__builtin_amdgcn_readfirstlane(kdst+(slot)))
;   #define DMA_V(t,slot) glds16(vsrc+(long)(t)*KVBLK*vp,(unsigned)__builtin_amdgcn_readfirstlane(vdst+(slot)))
;   #define MF(k,q,c) __builtin_amdgcn_mfma_f32_32x32x16_bf16(k,q,c,0,0,0)
;   #define X4(P,B) do{ P[B]=__builtin_amdgcn_exp2f(P[B]); P[B+1]=__builtin_amdgcn_exp2f(P[B+1]); P[B+2]=__builtin_amdgcn_exp2f(P[B+2]); P[B+3]=__builtin_amdgcn_exp2f(P[B+3]); asm volatile("":"+v"(P)); SBAR(); }while(0)
;   #define SP4(SUM,P,B,PW,H) do{ SUM+=P[B]; SUM+=P[B+1]; SUM+=P[B+2]; SUM+=P[B+3]; asm volatile("":"+v"(SUM)); PW[(H)*2]=cvtpk_s(P[B],P[B+1]); PW[(H)*2+1]=cvtpk_s(P[B+2],P[B+3]); asm volatile("":"+v"(PW)); SBAR(); }while(0)
; __device__ __forceinline__ void attn_unit2(const bf16*Qu,int qp,const bf16*__restrict__ Kh,int kp,const bf16*__restrict__ Vh,int vp,bf16*Ou,int op,int NT,char*shm,int tid_in){
;     ...
;   for(int d0=0;d0<4;++d0){ a0=MF(kf[2*d0],qa[d0],d0==0?z16:a0); a1=MF(kf[2*d0+1],qa[d0],d0==0?z16:a1); }
;   #pragma unroll
;   for(int r=0;r<16;++r){a0[r]=__builtin_amdgcn_exp2f(a0[r]);a1[r]=__builtin_amdgcn_exp2f(a1[r]);}
;   for(int t=0;t<NT;++t){
;     if(t>0){ if(t+2<NT) asm volatile("s_waitcnt vmcnt(2) lgkmcnt(0)\n\ts_barrier":::"memory"); else asm volatile("s_waitcnt vmcnt(0) lgkmcnt(0)\n\ts_barrier":::"memory"); }
;     if(t+3<NT){DMA_K(t+3,sl_n3);DMA_V(t+3,sl_n3);}
;     const bool nx=t+1<NT; const lds_cptr vq=vp0+sl_cur; s16x4 vlo[8],vhi[8]; float sa=0.f,sb=0.f;
;     ...
;     b0=MF(kf[0],qb[0],z16); SP4(sa,a0,0,pa[0],0);  b1=MF(kf[1],qb[0],z16); SP4(sa,a0,4,pa[0],1);
;     b0=MF(kf[2],qb[1],b0);  SP4(sa,a0,8,pa[1],0);  b1=MF(kf[3],qb[1],b1);  SP4(sa,a0,12,pa[1],1);
;     b0=MF(kf[4],qb[2],b0);  SP4(sa,a1,0,pa[2],0);  b1=MF(kf[5],qb[2],b1);  SP4(sa,a1,4,pa[2],1);
;     b0=MF(kf[6],qb[3],b0);  SP4(sa,a1,8,pa[3],0);  b1=MF(kf[7],qb[3],b1);  SP4(sa,a1,12,pa[3],1);
;     la+=sa;
;     VLD(); if(nx) kload8(kf,kp0+sl_n1);
;     ...
;     PVA(0,0); X4(b0,0); PVA(0,1); X4(b0,4); PVA(1,0); X4(b0,8); PVA(1,1); X4(b0,12);
;     PVA(2,0); X4(b1,0); PVA(2,1); X4(b1,4); PVA(3,0); X4(b1,8); PVA(3,1); X4(b1,12);
	v_mfma_f32_32x32x16_bf16 v[18:33], v[86:89], v[182:185], v[18:33]
	s_nop 9
	v_exp_f32_e32 v43, v2
	v_exp_f32_e32 v45, v3
	v_exp_f32_e32 v46, v4
	v_exp_f32_e32 v47, v5
	v_lshl_add_u64 v[2:3], v[100:101], 0, s[8:9]
	v_lshl_add_u64 v[4:5], v[98:99], 0, s[8:9]
	s_add_i32 s8, s3, 0x6000
	s_mov_b32 s9, m0
	s_mov_b32 m0, s8
	s_nop 0
	global_load_lds_dwordx4 v[4:5], off
	s_mov_b32 m0, s9
	v_exp_f32_e32 v18, v18
	v_exp_f32_e32 v19, v19
	v_exp_f32_e32 v20, v20
	v_exp_f32_e32 v21, v21
	v_exp_f32_e32 v6, v6
	v_exp_f32_e32 v22, v22
	v_exp_f32_e32 v7, v7
	v_exp_f32_e32 v23, v23
	v_exp_f32_e32 v8, v8
	v_exp_f32_e32 v24, v24
	v_exp_f32_e32 v9, v9
	v_exp_f32_e32 v25, v25
	v_exp_f32_e32 v10, v10
	v_exp_f32_e32 v26, v26
	v_exp_f32_e32 v11, v11
	v_exp_f32_e32 v27, v27
	v_exp_f32_e32 v12, v12
	v_exp_f32_e32 v28, v28
	v_exp_f32_e32 v13, v13
	v_exp_f32_e32 v29, v29
	v_exp_f32_e32 v14, v14
	v_exp_f32_e32 v30, v30
	v_exp_f32_e32 v15, v15
	v_exp_f32_e32 v31, v31
	v_exp_f32_e32 v16, v16
	v_exp_f32_e32 v32, v32
	v_exp_f32_e32 v17, v17
	v_exp_f32_e32 v33, v33
	s_add_i32 s8, s3, 0xe000
	s_mov_b32 s9, m0
	s_mov_b32 m0, s8
	s_nop 0
	global_load_lds_dwordx4 v[2:3], off
	s_mov_b32 m0, s9
	v_add_f32_e32 v2, 0, v43
	v_add_f32_e32 v2, v45, v2
	v_add_f32_e32 v2, v46, v2
	v_add_f32_e32 v2, v47, v2
	v_cvt_pk_bf16_f32 v158, v43, v45
	v_cvt_pk_bf16_f32 v159, v46, v47
	s_nop 0
	v_add_f32_e32 v2, v6, v2
	v_add_f32_e32 v2, v7, v2
	v_add_f32_e32 v2, v8, v2
	v_add_f32_e32 v2, v9, v2
	v_cvt_pk_bf16_f32 v160, v6, v7
	v_cvt_pk_bf16_f32 v161, v8, v9
	s_nop 0
	v_add_f32_e32 v2, v10, v2
	v_add_f32_e32 v2, v11, v2
	v_add_f32_e32 v2, v12, v2
	v_add_f32_e32 v2, v13, v2
	v_cvt_pk_bf16_f32 v154, v10, v11
	v_cvt_pk_bf16_f32 v155, v12, v13
	s_nop 0
	v_add_f32_e32 v2, v14, v2
	v_add_f32_e32 v2, v15, v2
	v_add_f32_e32 v2, v16, v2
	v_add_f32_e32 v2, v17, v2
	v_cvt_pk_bf16_f32 v156, v14, v15
	v_cvt_pk_bf16_f32 v157, v16, v17
	s_nop 0
	v_add_f32_e32 v2, v18, v2
	v_add_f32_e32 v2, v19, v2
	v_add_f32_e32 v2, v20, v2
	v_add_f32_e32 v2, v21, v2
	v_cvt_pk_bf16_f32 v138, v18, v19
	v_cvt_pk_bf16_f32 v139, v20, v21
	s_nop 0
	v_add_f32_e32 v2, v22, v2
	v_add_f32_e32 v2, v23, v2
	v_add_f32_e32 v2, v24, v2
	v_add_f32_e32 v2, v25, v2
	v_cvt_pk_bf16_f32 v140, v22, v23
	v_cvt_pk_bf16_f32 v141, v24, v25
	s_nop 0
	v_add_f32_e32 v2, v26, v2
	v_add_f32_e32 v2, v27, v2
	v_add_f32_e32 v2, v28, v2
	v_add_f32_e32 v2, v29, v2
	v_cvt_pk_bf16_f32 v134, v26, v27
	v_cvt_pk_bf16_f32 v135, v28, v29
	s_nop 0
	v_add_f32_e32 v2, v30, v2
	v_add_f32_e32 v2, v31, v2
	v_add_f32_e32 v2, v32, v2
	v_add_f32_e32 v102, v33, v2
	v_cvt_pk_bf16_f32 v136, v30, v31
	v_cvt_pk_bf16_f32 v137, v32, v33
	s_waitcnt vmcnt(3)
	v_mfma_f32_32x32x16_bf16 v[50:65], v[34:37], v[150:153], 0
	v_mfma_f32_32x32x16_bf16 v[34:49], v[38:41], v[150:153], 0
	s_waitcnt vmcnt(2)
	v_mfma_f32_32x32x16_bf16 v[50:65], v[66:69], v[146:149], v[50:65]
	ds_read_b64_tr_b16 v[2:3], v0 offset:32768
	ds_read_b64_tr_b16 v[4:5], v0 offset:33280
	ds_read_b64_tr_b16 v[66:67], v0 offset:33792
	ds_read_b64_tr_b16 v[68:69], v0 offset:34304
	v_mfma_f32_32x32x16_bf16 v[34:49], v[70:73], v[146:149], v[34:49]
	s_waitcnt vmcnt(1)
	v_mfma_f32_32x32x16_bf16 v[50:65], v[74:77], v[142:145], v[50:65]
	v_mfma_f32_32x32x16_bf16 v[34:49], v[78:81], v[142:145], v[34:49]
	ds_read_b64_tr_b16 v[70:71], v0 offset:34816
	ds_read_b64_tr_b16 v[72:73], v0 offset:35328
	ds_read_b64_tr_b16 v[74:75], v0 offset:35840
	ds_read_b64_tr_b16 v[76:77], v0 offset:36352
	ds_read_b64_tr_b16 v[18:19], v0 offset:36864
	ds_read_b64_tr_b16 v[20:21], v0 offset:37376
	ds_read_b64_tr_b16 v[78:79], v0 offset:37888
	ds_read_b64_tr_b16 v[80:81], v0 offset:38400
	s_waitcnt vmcnt(0)
	v_mfma_f32_32x32x16_bf16 v[50:65], v[82:85], v[130:133], v[50:65]
	ds_read_b64_tr_b16 v[82:83], v0 offset:38912
	ds_read_b64_tr_b16 v[84:85], v0 offset:39424
	ds_read_b64_tr_b16 v[90:91], v0 offset:39936
	ds_read_b64_tr_b16 v[92:93], v0 offset:40448
	ds_read_b128 v[206:209], v241 offset:8192
	ds_read_b128 v[210:213], v241 offset:8704
	ds_read_b128 v[202:205], v241 offset:10240
	ds_read_b128 v[198:201], v241 offset:10752
	ds_read_b128 v[222:225], v241 offset:12288
	ds_read_b128 v[218:221], v241 offset:12800
	ds_read_b128 v[214:217], v241 offset:14336
	ds_read_b128 v[194:197], v241 offset:14848
	v_exp_f32_e32 v50, v50
	v_mfma_f32_32x32x16_bf16 v[34:49], v[86:89], v[130:133], v[34:49]
	v_exp_f32_e32 v51, v51
	v_exp_f32_e32 v52, v52
	v_exp_f32_e32 v53, v53
	s_waitcnt lgkmcnt(14)
	v_mfma_f32_32x32x16_bf16 v[2:17], v[158:161], v[2:5], 0
	v_mfma_f32_32x32x16_bf16 v[18:33], v[158:161], v[18:21], 0
	v_exp_f32_e32 v54, v54
	v_exp_f32_e32 v55, v55
	v_exp_f32_e32 v56, v56
	v_exp_f32_e32 v57, v57
	v_mfma_f32_32x32x16_bf16 v[2:17], v[154:157], v[66:69], v[2:17]
	v_exp_f32_e32 v58, v58
	v_exp_f32_e32 v59, v59
	v_exp_f32_e32 v60, v60
	v_exp_f32_e32 v61, v61
	s_waitcnt lgkmcnt(12)
	v_mfma_f32_32x32x16_bf16 v[18:33], v[154:157], v[78:81], v[18:33]
	v_exp_f32_e32 v62, v62
	v_exp_f32_e32 v63, v63
	v_exp_f32_e32 v64, v64
	v_exp_f32_e32 v65, v65
	v_mfma_f32_32x32x16_bf16 v[2:17], v[138:141], v[70:73], v[2:17]
	v_exp_f32_e32 v34, v34
	v_exp_f32_e32 v35, v35
	v_exp_f32_e32 v36, v36
	v_exp_f32_e32 v37, v37
	s_waitcnt lgkmcnt(10)
	v_mfma_f32_32x32x16_bf16 v[18:33], v[138:141], v[82:85], v[18:33]
	v_exp_f32_e32 v38, v38
	v_exp_f32_e32 v39, v39
	v_exp_f32_e32 v40, v40
	v_exp_f32_e32 v41, v41
	v_mfma_f32_32x32x16_bf16 v[2:17], v[134:137], v[74:77], v[2:17]
	v_exp_f32_e32 v42, v42
	v_exp_f32_e32 v43, v43
	v_exp_f32_e32 v44, v44
	v_exp_f32_e32 v45, v45
	s_waitcnt lgkmcnt(8)
	v_mfma_f32_32x32x16_bf16 v[18:33], v[134:137], v[90:93], v[18:33]
	v_exp_f32_e32 v46, v46
	v_exp_f32_e32 v47, v47
	v_exp_f32_e32 v48, v48
	v_exp_f32_e32 v49, v49
	s_waitcnt lgkmcnt(7)
; #define SBAR() __builtin_amdgcn_sched_barrier(0)
;   #define DMA_K(t,slot) glds16(ksrc+(long)(t)*KVBLK*kp,(unsigned)__builtin_amdgcn_readfirstlane(kdst+(slot)))
;   #define DMA_V(t,slot) glds16(vsrc+(long)(t)*KVBLK*vp,(unsigned)__builtin_amdgcn_readfirstlane(vdst+(slot)))
;   #define DMA_K(t,slot) glds16(ksrc+(long)(t)*KVBLK*kp,(unsigned)__builtin_amdgcn_readfirstlane(kdst+(slot)))
;   #define MF(k,q,c) __builtin_amdgcn_mfma_f32_32x32x16_bf16(k,q,c,0,0,0)
; __device__ __forceinline__ void attn_unit2(const bf16*Qu,int qp,const bf16*__restrict__ Kh,int kp,const bf16*__restrict__ Vh,int vp,bf16*Ou,int op,int NT,char*shm,int tid_in){
;     ...
;   for(int t=0;t<NT;++t){
;     if(t>0){ if(t+2<NT) asm volatile("s_waitcnt vmcnt(2) lgkmcnt(0)\n\ts_barrier":::"memory"); else asm volatile("s_waitcnt vmcnt(0) lgkmcnt(0)\n\ts_barrier":::"memory"); }
;     if(t+3<NT){DMA_K(t+3,sl_n3);DMA_V(t+3,sl_n3);}
;     const bool nx=t+1<NT; const lds_cptr vq=vp0+sl_cur; s16x4 vlo[8],vhi[8]; float sa=0.f,sb=0.f;
;     ...
;     b0=MF(kf[0],qb[0],z16); SP4(sa,a0,0,pa[0],0);  b1=MF(kf[1],qb[0],z16); SP4(sa,a0,4,pa[0],1);
;     b0=MF(kf[2],qb[1],b0);  SP4(sa,a0,8,pa[1],0);  b1=MF(kf[3],qb[1],b1);  SP4(sa,a0,12,pa[1],1);
;     b0=MF(kf[4],qb[2],b0);  SP4(sa,a1,0,pa[2],0);  b1=MF(kf[5],qb[2],b1);  SP4(sa,a1,4,pa[2],1);
;     b0=MF(kf[6],qb[3],b0);  SP4(sa,a1,8,pa[3],0);  b1=MF(kf[7],qb[3],b1);  SP4(sa,a1,12,pa[3],1);
;     la+=sa;
;     VLD(); if(nx) kload8(kf,kp0+sl_n1);
;     ...
;     PVA(0,0); X4(b0,0); PVA(0,1); X4(b0,4); PVA(1,0); X4(b0,8); PVA(1,1); X4(b0,12);
;     PVA(2,0); X4(b1,0); PVA(2,1); X4(b1,4); PVA(3,0); X4(b1,8); PVA(3,1); X4(b1,12);
;     if(nx){ a0=MF(kf[0],qa[0],z16); } SP4(sb,b0,0,pb[0],0);  if(nx){ a1=MF(kf[1],qa[0],z16); } SP4(sb,b0,4,pb[0],1);
;     if(nx){ a0=MF(kf[2],qa[1],a0); }  SP4(sb,b0,8,pb[1],0);  if(nx){ a1=MF(kf[3],qa[1],a1); }  SP4(sb,b0,12,pb[1],1);
;     if(nx){ a0=MF(kf[4],qa[2],a0); }  SP4(sb,b1,0,pb[2],0);  if(nx){ a1=MF(kf[5],qa[2],a1); }  SP4(sb,b1,4,pb[2],1);
;     if(nx){ a0=MF(kf[6],qa[3],a0); }  SP4(sb,b1,8,pb[3],0);  if(nx){ a1=MF(kf[7],qa[3],a1); }  SP4(sb,b1,12,pb[3],1);
;     lb+=sb;
;     VLD(); SBAR();
;     PVB(0,0); if(nx) X4(a0,0); PVB(0,1); if(nx) X4(a0,4); PVB(1,0); if(nx) X4(a0,8); PVB(1,1); if(nx) X4(a0,12);
;     PVB(2,0); if(nx) X4(a1,0); PVB(2,1); if(nx) X4(a1,4); PVB(3,0); if(nx) X4(a1,8); PVB(3,1); if(nx) X4(a1,12);
	v_mfma_f32_32x32x16_bf16 v[82:97], v[206:209], v[170:173], 0
	v_add_f32_e32 v66, 0, v50
	v_add_f32_e32 v66, v51, v66
	v_add_f32_e32 v66, v52, v66
	v_add_f32_e32 v66, v53, v66
	v_cvt_pk_bf16_f32 v162, v50, v51
	v_cvt_pk_bf16_f32 v163, v52, v53
	s_nop 0
	v_add_f32_e32 v50, v54, v66
	s_waitcnt lgkmcnt(6)
	v_mfma_f32_32x32x16_bf16 v[66:81], v[210:213], v[170:173], 0
	v_add_f32_e32 v50, v55, v50
	v_add_f32_e32 v50, v56, v50
	v_add_f32_e32 v50, v57, v50
	v_cvt_pk_bf16_f32 v164, v54, v55
	v_cvt_pk_bf16_f32 v165, v56, v57
	s_waitcnt lgkmcnt(5)
	v_mfma_f32_32x32x16_bf16 v[82:97], v[202:205], v[174:177], v[82:97]
	v_add_f32_e32 v50, v58, v50
	v_add_f32_e32 v50, v59, v50
	v_add_f32_e32 v50, v60, v50
	v_add_f32_e32 v50, v61, v50
	v_cvt_pk_bf16_f32 v166, v58, v59
	v_cvt_pk_bf16_f32 v167, v60, v61
	s_waitcnt lgkmcnt(4)
	v_mfma_f32_32x32x16_bf16 v[66:81], v[198:201], v[174:177], v[66:81]
	v_add_f32_e32 v50, v62, v50
	v_add_f32_e32 v50, v63, v50
	v_add_f32_e32 v50, v64, v50
	v_add_f32_e32 v50, v65, v50
	v_cvt_pk_bf16_f32 v168, v62, v63
	v_cvt_pk_bf16_f32 v169, v64, v65
	s_waitcnt lgkmcnt(3)
	v_mfma_f32_32x32x16_bf16 v[82:97], v[222:225], v[178:181], v[82:97]
	v_add_f32_e32 v50, v34, v50
	v_add_f32_e32 v50, v35, v50
	v_add_f32_e32 v50, v36, v50
	v_add_f32_e32 v50, v37, v50
	v_cvt_pk_bf16_f32 v186, v34, v35
	v_cvt_pk_bf16_f32 v187, v36, v37
	s_waitcnt lgkmcnt(2)
	v_mfma_f32_32x32x16_bf16 v[66:81], v[218:221], v[178:181], v[66:81]
	v_add_f32_e32 v34, v38, v50
	v_add_f32_e32 v34, v39, v34
	v_add_f32_e32 v34, v40, v34
	v_add_f32_e32 v34, v41, v34
	v_cvt_pk_bf16_f32 v188, v38, v39
	v_cvt_pk_bf16_f32 v189, v40, v41
	s_waitcnt lgkmcnt(1)
	v_mfma_f32_32x32x16_bf16 v[82:97], v[214:217], v[182:185], v[82:97]
	v_add_f32_e32 v34, v42, v34
	v_add_f32_e32 v34, v43, v34
	v_add_f32_e32 v34, v44, v34
	v_add_f32_e32 v34, v45, v34
	v_cvt_pk_bf16_f32 v190, v42, v43
	v_cvt_pk_bf16_f32 v191, v44, v45
	s_waitcnt lgkmcnt(0)
	v_mfma_f32_32x32x16_bf16 v[66:81], v[194:197], v[182:185], v[66:81]
	v_add_f32_e32 v34, v46, v34
	v_add_f32_e32 v34, v47, v34
	v_add_f32_e32 v34, v48, v34
	v_add_f32_e32 v103, v49, v34
	v_cvt_pk_bf16_f32 v192, v46, v47
	v_cvt_pk_bf16_f32 v193, v48, v49
	ds_read_b64_tr_b16 v[34:35], v0 offset:32768
	ds_read_b64_tr_b16 v[36:37], v0 offset:33280
	ds_read_b64_tr_b16 v[104:105], v0 offset:33792
	ds_read_b64_tr_b16 v[106:107], v0 offset:34304
	ds_read_b64_tr_b16 v[108:109], v0 offset:34816
	ds_read_b64_tr_b16 v[110:111], v0 offset:35328
	ds_read_b64_tr_b16 v[112:113], v0 offset:35840
	ds_read_b64_tr_b16 v[114:115], v0 offset:36352
	ds_read_b64_tr_b16 v[50:51], v0 offset:36864
	ds_read_b64_tr_b16 v[52:53], v0 offset:37376
	ds_read_b64_tr_b16 v[116:117], v0 offset:37888
	ds_read_b64_tr_b16 v[118:119], v0 offset:38400
	ds_read_b64_tr_b16 v[120:121], v0 offset:38912
	ds_read_b64_tr_b16 v[122:123], v0 offset:39424
	ds_read_b64_tr_b16 v[124:125], v0 offset:39936
	ds_read_b64_tr_b16 v[126:127], v0 offset:40448
	v_pk_add_f32 v[226:227], v[102:103], 0 op_sel_hi:[1,0]
	s_waitcnt lgkmcnt(14)
	v_mfma_f32_32x32x16_bf16 v[34:49], v[162:165], v[34:37], 0
	v_exp_f32_e32 v82, v82
	v_exp_f32_e32 v83, v83
	v_exp_f32_e32 v84, v84
	v_exp_f32_e32 v85, v85
	s_waitcnt lgkmcnt(6)
	v_mfma_f32_32x32x16_bf16 v[50:65], v[162:165], v[50:53], 0
	v_exp_f32_e32 v86, v86
	v_exp_f32_e32 v87, v87
	v_exp_f32_e32 v88, v88
	v_exp_f32_e32 v89, v89
	v_mfma_f32_32x32x16_bf16 v[34:49], v[166:169], v[104:107], v[34:49]
	v_exp_f32_e32 v90, v90
	v_exp_f32_e32 v91, v91
	v_exp_f32_e32 v92, v92
	v_exp_f32_e32 v93, v93
	s_waitcnt lgkmcnt(4)
	v_mfma_f32_32x32x16_bf16 v[50:65], v[166:169], v[116:119], v[50:65]
	v_exp_f32_e32 v94, v94
	v_exp_f32_e32 v95, v95
	v_exp_f32_e32 v96, v96
	v_exp_f32_e32 v97, v97
	v_mfma_f32_32x32x16_bf16 v[34:49], v[186:189], v[108:111], v[34:49]
	v_exp_f32_e32 v66, v66
	v_exp_f32_e32 v67, v67
	v_exp_f32_e32 v68, v68
	v_exp_f32_e32 v69, v69
	s_waitcnt lgkmcnt(2)
	v_mfma_f32_32x32x16_bf16 v[50:65], v[186:189], v[120:123], v[50:65]
	v_exp_f32_e32 v70, v70
	v_exp_f32_e32 v71, v71
	v_exp_f32_e32 v72, v72
	v_exp_f32_e32 v73, v73
	v_mfma_f32_32x32x16_bf16 v[34:49], v[190:193], v[112:115], v[34:49]
	v_exp_f32_e32 v74, v74
	v_exp_f32_e32 v75, v75
	v_exp_f32_e32 v76, v76
	v_exp_f32_e32 v77, v77
	s_waitcnt lgkmcnt(0)
	v_mfma_f32_32x32x16_bf16 v[50:65], v[190:193], v[124:127], v[50:65]
	v_exp_f32_e32 v78, v78
	v_exp_f32_e32 v79, v79
	v_exp_f32_e32 v80, v80
	v_exp_f32_e32 v81, v81
	s_mov_b64 s[8:9], 0x10000
	v_lshl_add_u64 v[228:229], v[98:99], 0, s[8:9]
	v_lshl_add_u64 v[230:231], v[100:101], 0, s[8:9]
	s_nop 0
	v_readfirstlane_b32 s20, v228
	v_readfirstlane_b32 s21, v229
	v_readfirstlane_b32 s22, v230
	v_readfirstlane_b32 s23, v231
	s_nop 1
	v_subrev_u32_e32 v228, s20, v228
	v_subrev_u32_e32 v230, s22, v230
	v_add_u32_e32 v228, 0x100000, v228
	v_add_u32_e32 v230, 0x100000, v230
	s_sub_u32 s20, s20, 0x100000
	s_subb_u32 s21, s21, 0
	s_sub_u32 s22, s22, 0x100000
	s_subb_u32 s23, s23, 0
	s_branch .LBB0_897
;   #define MF(k,q,c) __builtin_amdgcn_mfma_f32_32x32x16_bf16(k,q,c,0,0,0)
;   #define X4(P,B) do{ P[B]=__builtin_amdgcn_exp2f(P[B]); P[B+1]=__builtin_amdgcn_exp2f(P[B+1]); P[B+2]=__builtin_amdgcn_exp2f(P[B+2]); P[B+3]=__builtin_amdgcn_exp2f(P[B+3]); asm volatile("":"+v"(P)); SBAR(); }while(0)
;   #define SP4(SUM,P,B,PW,H) do{ SUM+=P[B]; SUM+=P[B+1]; SUM+=P[B+2]; SUM+=P[B+3]; asm volatile("":"+v"(SUM)); PW[(H)*2]=cvtpk_s(P[B],P[B+1]); PW[(H)*2+1]=cvtpk_s(P[B+2],P[B+3]); asm volatile("":"+v"(PW)); SBAR(); }while(0)
;     #define VLD() do{ _Pragma("unroll") for(int i=0;i<8;++i){ vlo[i]=vtr(vq+((i>>2)*4096+(i&3)*1024)); vhi[i]=vtr(vq+((i>>2)*4096+(i&3)*1024+512)); } }while(0)
;     #define PVA(ks,d0) oa[d0]=MF(__builtin_bit_cast(bf16x8,pa[ks]),VF((ks)+4*(d0)),oa[d0])
; __device__ __forceinline__ void attn_unit2(const bf16*Qu,int qp,const bf16*__restrict__ Kh,int kp,const bf16*__restrict__ Vh,int vp,bf16*Ou,int op,int NT,char*shm,int tid_in){
;     ...
;     const bool nx=t+1<NT; const lds_cptr vq=vp0+sl_cur; s16x4 vlo[8],vhi[8]; float sa=0.f,sb=0.f;
;     ...
;     b0=MF(kf[0],qb[0],z16); SP4(sa,a0,0,pa[0],0);  b1=MF(kf[1],qb[0],z16); SP4(sa,a0,4,pa[0],1);
;     b0=MF(kf[2],qb[1],b0);  SP4(sa,a0,8,pa[1],0);  b1=MF(kf[3],qb[1],b1);  SP4(sa,a0,12,pa[1],1);
;     b0=MF(kf[4],qb[2],b0);  SP4(sa,a1,0,pa[2],0);  b1=MF(kf[5],qb[2],b1);  SP4(sa,a1,4,pa[2],1);
;     b0=MF(kf[6],qb[3],b0);  SP4(sa,a1,8,pa[3],0);  b1=MF(kf[7],qb[3],b1);  SP4(sa,a1,12,pa[3],1);
;     la+=sa;
;     VLD(); if(nx) kload8(kf,kp0+sl_n1);
;     ...
;     PVA(0,0); X4(b0,0); PVA(0,1); X4(b0,4); PVA(1,0); X4(b0,8); PVA(1,1); X4(b0,12);
;     PVA(2,0); X4(b1,0); PVA(2,1); X4(b1,4); PVA(3,0); X4(b1,8); PVA(3,1); X4(b1,12);
.LBB0_896:
	s_add_i32 s13, s13, 1
	v_add_u32_e32 v240, s14, v0
	v_mfma_f32_32x32x16_bf16 v[114:129], v[206:209], v[150:153], 0
	v_add_f32_e32 v232, 0, v82
	v_cvt_pk_bf16_f32 v158, v82, v83
	v_add_f32_e32 v232, v83, v232
	v_add_f32_e32 v232, v84, v232
	v_cvt_pk_bf16_f32 v159, v84, v85
	v_add_f32_e32 v232, v85, v232
	ds_read_b64_tr_b16 v[82:83], v240 offset:36864
	ds_read_b64_tr_b16 v[84:85], v240 offset:37376
	v_mfma_f32_32x32x16_bf16 v[98:113], v[210:213], v[150:153], 0
	v_add_f32_e32 v232, v86, v232
	v_cvt_pk_bf16_f32 v160, v86, v87
	v_add_f32_e32 v232, v87, v232
	v_add_f32_e32 v232, v88, v232
	v_cvt_pk_bf16_f32 v161, v88, v89
	v_add_f32_e32 v232, v89, v232
	ds_read_b64_tr_b16 v[86:87], v240 offset:37888
	ds_read_b64_tr_b16 v[88:89], v240 offset:38400
	v_mfma_f32_32x32x16_bf16 v[114:129], v[202:205], v[146:149], v[114:129]
	v_add_f32_e32 v232, v90, v232
	v_cvt_pk_bf16_f32 v154, v90, v91
	v_add_f32_e32 v232, v91, v232
	v_add_f32_e32 v232, v92, v232
	v_cvt_pk_bf16_f32 v155, v92, v93
	v_add_f32_e32 v232, v93, v232
	ds_read_b64_tr_b16 v[90:91], v240 offset:38912
	ds_read_b64_tr_b16 v[92:93], v240 offset:39424
	v_mfma_f32_32x32x16_bf16 v[98:113], v[198:201], v[146:149], v[98:113]
	v_add_f32_e32 v232, v94, v232
	v_cvt_pk_bf16_f32 v156, v94, v95
	v_add_f32_e32 v232, v95, v232
	v_add_f32_e32 v232, v96, v232
	v_cvt_pk_bf16_f32 v157, v96, v97
	v_add_f32_e32 v232, v97, v232
	ds_read_b64_tr_b16 v[94:95], v240 offset:39936
	ds_read_b64_tr_b16 v[96:97], v240 offset:40448
	v_mfma_f32_32x32x16_bf16 v[114:129], v[222:225], v[142:145], v[114:129]
	v_add_f32_e32 v232, v66, v232
	v_cvt_pk_bf16_f32 v138, v66, v67
	v_add_f32_e32 v232, v67, v232
	v_add_f32_e32 v232, v68, v232
	v_cvt_pk_bf16_f32 v139, v68, v69
	v_add_f32_e32 v232, v69, v232
	ds_read_b64_tr_b16 v[66:67], v240 offset:32768
	ds_read_b64_tr_b16 v[68:69], v240 offset:33280
	v_mfma_f32_32x32x16_bf16 v[98:113], v[218:221], v[142:145], v[98:113]
	v_add_f32_e32 v232, v70, v232
	v_cvt_pk_bf16_f32 v140, v70, v71
	v_add_f32_e32 v232, v71, v232
	v_add_f32_e32 v232, v72, v232
	v_cvt_pk_bf16_f32 v141, v72, v73
	v_add_f32_e32 v232, v73, v232
	ds_read_b64_tr_b16 v[70:71], v240 offset:33792
	ds_read_b64_tr_b16 v[72:73], v240 offset:34304
	v_mfma_f32_32x32x16_bf16 v[114:129], v[214:217], v[130:133], v[114:129]
	v_add_f32_e32 v232, v74, v232
	v_cvt_pk_bf16_f32 v134, v74, v75
	v_add_f32_e32 v232, v75, v232
	v_add_f32_e32 v232, v76, v232
	v_cvt_pk_bf16_f32 v135, v76, v77
	v_add_f32_e32 v232, v77, v232
	ds_read_b64_tr_b16 v[74:75], v240 offset:34816
	ds_read_b64_tr_b16 v[76:77], v240 offset:35328
	v_mfma_f32_32x32x16_bf16 v[98:113], v[194:197], v[130:133], v[98:113]
	v_add_f32_e32 v232, v78, v232
	v_cvt_pk_bf16_f32 v136, v78, v79
	v_add_f32_e32 v232, v79, v232
	v_add_f32_e32 v232, v80, v232
	v_cvt_pk_bf16_f32 v137, v80, v81
	v_add_f32_e32 v232, v81, v232
	ds_read_b64_tr_b16 v[78:79], v240 offset:35840
	ds_read_b64_tr_b16 v[80:81], v240 offset:36352
	v_add_u32_e32 v162, s16, v241
	ds_read_b128 v[206:209], v162
	ds_read_b128 v[210:213], v162 offset:512
	ds_read_b128 v[202:205], v162 offset:2048
	ds_read_b128 v[198:201], v162 offset:2560
	ds_read_b128 v[222:225], v162 offset:4096
	ds_read_b128 v[218:221], v162 offset:4608
	ds_read_b128 v[214:217], v162 offset:6144
	ds_read_b128 v[194:197], v162 offset:6656
	s_waitcnt lgkmcnt(14)
	v_mfma_f32_32x32x16_bf16 v[2:17], v[158:161], v[66:69], v[2:17]
	v_exp_f32_e32 v114, v114
	v_exp_f32_e32 v115, v115
	v_exp_f32_e32 v116, v116
	v_exp_f32_e32 v117, v117
	s_waitcnt lgkmcnt(14)
	v_mfma_f32_32x32x16_bf16 v[18:33], v[158:161], v[82:85], v[18:33]
	v_exp_f32_e32 v118, v118
	v_exp_f32_e32 v119, v119
	v_exp_f32_e32 v120, v120
	v_exp_f32_e32 v121, v121
	s_waitcnt lgkmcnt(12)
	v_mfma_f32_32x32x16_bf16 v[2:17], v[154:157], v[70:73], v[2:17]
	v_exp_f32_e32 v122, v122
	v_exp_f32_e32 v123, v123
	v_exp_f32_e32 v124, v124
	v_exp_f32_e32 v125, v125
	s_waitcnt lgkmcnt(12)
	v_mfma_f32_32x32x16_bf16 v[18:33], v[154:157], v[86:89], v[18:33]
	v_exp_f32_e32 v126, v126
	v_exp_f32_e32 v127, v127
	v_exp_f32_e32 v128, v128
	v_exp_f32_e32 v129, v129
	s_waitcnt lgkmcnt(10)
	v_mfma_f32_32x32x16_bf16 v[2:17], v[138:141], v[74:77], v[2:17]
	v_exp_f32_e32 v98, v98
	v_exp_f32_e32 v99, v99
	v_exp_f32_e32 v100, v100
	v_exp_f32_e32 v101, v101
	s_waitcnt lgkmcnt(10)
	v_mfma_f32_32x32x16_bf16 v[18:33], v[138:141], v[90:93], v[18:33]
	v_exp_f32_e32 v102, v102
	v_exp_f32_e32 v103, v103
	v_exp_f32_e32 v104, v104
	v_exp_f32_e32 v105, v105
	s_waitcnt lgkmcnt(8)
	v_mfma_f32_32x32x16_bf16 v[2:17], v[134:137], v[78:81], v[2:17]
	v_exp_f32_e32 v106, v106
	v_exp_f32_e32 v107, v107
	v_exp_f32_e32 v108, v108
	v_exp_f32_e32 v109, v109
	s_waitcnt lgkmcnt(8)
	v_mfma_f32_32x32x16_bf16 v[18:33], v[134:137], v[94:97], v[18:33]
	v_exp_f32_e32 v110, v110
	v_exp_f32_e32 v111, v111
	v_exp_f32_e32 v112, v112
	v_exp_f32_e32 v113, v113
	s_waitcnt lgkmcnt(7)
; #define SBAR() __builtin_amdgcn_sched_barrier(0)
;   #define MF(k,q,c) __builtin_amdgcn_mfma_f32_32x32x16_bf16(k,q,c,0,0,0)
;   #define X4(P,B) do{ P[B]=__builtin_amdgcn_exp2f(P[B]); P[B+1]=__builtin_amdgcn_exp2f(P[B+1]); P[B+2]=__builtin_amdgcn_exp2f(P[B+2]); P[B+3]=__builtin_amdgcn_exp2f(P[B+3]); asm volatile("":"+v"(P)); SBAR(); }while(0)
;   #define SP4(SUM,P,B,PW,H) do{ SUM+=P[B]; SUM+=P[B+1]; SUM+=P[B+2]; SUM+=P[B+3]; asm volatile("":"+v"(SUM)); PW[(H)*2]=cvtpk_s(P[B],P[B+1]); PW[(H)*2+1]=cvtpk_s(P[B+2],P[B+3]); asm volatile("":"+v"(PW)); SBAR(); }while(0)
;     #define VLD() do{ _Pragma("unroll") for(int i=0;i<8;++i){ vlo[i]=vtr(vq+((i>>2)*4096+(i&3)*1024)); vhi[i]=vtr(vq+((i>>2)*4096+(i&3)*1024+512)); } }while(0)
;     #define PVB(ks,d0) ob[d0]=MF(__builtin_bit_cast(bf16x8,pb[ks]),VF((ks)+4*(d0)),ob[d0])
; __device__ __forceinline__ void attn_unit2(const bf16*Qu,int qp,const bf16*__restrict__ Kh,int kp,const bf16*__restrict__ Vh,int vp,bf16*Ou,int op,int NT,char*shm,int tid_in){
;     ...
;     if(nx){ a0=MF(kf[0],qa[0],z16); } SP4(sb,b0,0,pb[0],0);  if(nx){ a1=MF(kf[1],qa[0],z16); } SP4(sb,b0,4,pb[0],1);
;     if(nx){ a0=MF(kf[2],qa[1],a0); }  SP4(sb,b0,8,pb[1],0);  if(nx){ a1=MF(kf[3],qa[1],a1); }  SP4(sb,b0,12,pb[1],1);
;     if(nx){ a0=MF(kf[4],qa[2],a0); }  SP4(sb,b1,0,pb[2],0);  if(nx){ a1=MF(kf[5],qa[2],a1); }  SP4(sb,b1,4,pb[2],1);
;     if(nx){ a0=MF(kf[6],qa[3],a0); }  SP4(sb,b1,8,pb[3],0);  if(nx){ a1=MF(kf[7],qa[3],a1); }  SP4(sb,b1,12,pb[3],1);
;     lb+=sb;
;     VLD(); SBAR();
;     PVB(0,0); if(nx) X4(a0,0); PVB(0,1); if(nx) X4(a0,4); PVB(1,0); if(nx) X4(a0,8); PVB(1,1); if(nx) X4(a0,12);
;     PVB(2,0); if(nx) X4(a1,0); PVB(2,1); if(nx) X4(a1,4); PVB(3,0); if(nx) X4(a1,8); PVB(3,1); if(nx) X4(a1,12);
;     SBAR();
;     ...
;     sl_cur=(sl_cur==3*SLOTB)?0:sl_cur+SLOTB; sl_n1=(sl_n1==3*SLOTB)?0:sl_n1+SLOTB; sl_n3=(sl_n3==3*SLOTB)?0:sl_n3+SLOTB;
	v_mfma_f32_32x32x16_bf16 v[82:97], v[206:209], v[170:173], 0
	v_add_f32_e32 v233, 0, v114
	v_cvt_pk_bf16_f32 v162, v114, v115
	v_add_f32_e32 v233, v115, v233
	v_add_f32_e32 v233, v116, v233
	v_cvt_pk_bf16_f32 v163, v116, v117
	v_add_f32_e32 v233, v117, v233
	ds_read_b64_tr_b16 v[114:115], v240 offset:36864
	ds_read_b64_tr_b16 v[116:117], v240 offset:37376
	s_waitcnt lgkmcnt(8)
	v_mfma_f32_32x32x16_bf16 v[66:81], v[210:213], v[170:173], 0
	v_add_f32_e32 v233, v118, v233
	v_cvt_pk_bf16_f32 v164, v118, v119
	v_add_f32_e32 v233, v119, v233
	v_add_f32_e32 v233, v120, v233
	v_cvt_pk_bf16_f32 v165, v120, v121
	v_add_f32_e32 v233, v121, v233
	ds_read_b64_tr_b16 v[118:119], v240 offset:37888
	ds_read_b64_tr_b16 v[120:121], v240 offset:38400
	s_waitcnt lgkmcnt(9)
	v_mfma_f32_32x32x16_bf16 v[82:97], v[202:205], v[174:177], v[82:97]
	v_add_f32_e32 v233, v122, v233
	v_cvt_pk_bf16_f32 v166, v122, v123
	v_add_f32_e32 v233, v123, v233
	v_add_f32_e32 v233, v124, v233
	v_cvt_pk_bf16_f32 v167, v124, v125
	v_add_f32_e32 v233, v125, v233
	ds_read_b64_tr_b16 v[122:123], v240 offset:38912
	ds_read_b64_tr_b16 v[124:125], v240 offset:39424
	s_waitcnt lgkmcnt(10)
	v_mfma_f32_32x32x16_bf16 v[66:81], v[198:201], v[174:177], v[66:81]
	v_add_f32_e32 v233, v126, v233
	v_cvt_pk_bf16_f32 v168, v126, v127
	v_add_f32_e32 v233, v127, v233
	v_add_f32_e32 v233, v128, v233
	v_cvt_pk_bf16_f32 v169, v128, v129
	v_add_f32_e32 v233, v129, v233
	ds_read_b64_tr_b16 v[126:127], v240 offset:39936
	ds_read_b64_tr_b16 v[128:129], v240 offset:40448
	s_waitcnt lgkmcnt(11)
	v_mfma_f32_32x32x16_bf16 v[82:97], v[222:225], v[178:181], v[82:97]
	v_add_f32_e32 v233, v98, v233
	v_cvt_pk_bf16_f32 v186, v98, v99
	v_add_f32_e32 v233, v99, v233
	v_add_f32_e32 v233, v100, v233
	v_cvt_pk_bf16_f32 v187, v100, v101
	v_add_f32_e32 v233, v101, v233
	ds_read_b64_tr_b16 v[98:99], v240 offset:32768
	ds_read_b64_tr_b16 v[100:101], v240 offset:33280
	s_waitcnt lgkmcnt(12)
	v_mfma_f32_32x32x16_bf16 v[66:81], v[218:221], v[178:181], v[66:81]
	v_add_f32_e32 v233, v102, v233
	v_cvt_pk_bf16_f32 v188, v102, v103
	v_add_f32_e32 v233, v103, v233
	v_add_f32_e32 v233, v104, v233
	v_cvt_pk_bf16_f32 v189, v104, v105
	v_add_f32_e32 v233, v105, v233
	ds_read_b64_tr_b16 v[102:103], v240 offset:33792
	ds_read_b64_tr_b16 v[104:105], v240 offset:34304
	s_waitcnt lgkmcnt(13)
	v_mfma_f32_32x32x16_bf16 v[82:97], v[214:217], v[182:185], v[82:97]
	v_add_f32_e32 v233, v106, v233
	v_cvt_pk_bf16_f32 v190, v106, v107
	v_add_f32_e32 v233, v107, v233
	v_add_f32_e32 v233, v108, v233
	v_cvt_pk_bf16_f32 v191, v108, v109
	v_add_f32_e32 v233, v109, v233
	ds_read_b64_tr_b16 v[106:107], v240 offset:34816
	ds_read_b64_tr_b16 v[108:109], v240 offset:35328
	s_waitcnt lgkmcnt(14)
	v_mfma_f32_32x32x16_bf16 v[66:81], v[194:197], v[182:185], v[66:81]
	v_add_f32_e32 v233, v110, v233
	v_cvt_pk_bf16_f32 v192, v110, v111
	v_add_f32_e32 v233, v111, v233
	v_add_f32_e32 v233, v112, v233
	v_cvt_pk_bf16_f32 v193, v112, v113
	v_add_f32_e32 v233, v113, v233
	ds_read_b64_tr_b16 v[110:111], v240 offset:35840
	ds_read_b64_tr_b16 v[112:113], v240 offset:36352
	v_pk_add_f32 v[226:227], v[226:227], v[232:233]
	s_waitcnt lgkmcnt(6)
	v_mfma_f32_32x32x16_bf16 v[34:49], v[162:165], v[98:101], v[34:49]
	v_exp_f32_e32 v82, v82
	v_exp_f32_e32 v83, v83
	v_exp_f32_e32 v84, v84
	v_exp_f32_e32 v85, v85
	s_waitcnt lgkmcnt(6)
	v_mfma_f32_32x32x16_bf16 v[50:65], v[162:165], v[114:117], v[50:65]
	v_exp_f32_e32 v86, v86
	v_exp_f32_e32 v87, v87
	v_exp_f32_e32 v88, v88
	v_exp_f32_e32 v89, v89
	s_waitcnt lgkmcnt(4)
	v_mfma_f32_32x32x16_bf16 v[34:49], v[166:169], v[102:105], v[34:49]
	v_exp_f32_e32 v90, v90
	v_exp_f32_e32 v91, v91
	v_exp_f32_e32 v92, v92
	v_exp_f32_e32 v93, v93
	s_waitcnt lgkmcnt(4)
	v_mfma_f32_32x32x16_bf16 v[50:65], v[166:169], v[118:121], v[50:65]
	v_exp_f32_e32 v94, v94
	v_exp_f32_e32 v95, v95
	v_exp_f32_e32 v96, v96
	v_exp_f32_e32 v97, v97
	s_waitcnt lgkmcnt(2)
	v_mfma_f32_32x32x16_bf16 v[34:49], v[186:189], v[106:109], v[34:49]
	v_exp_f32_e32 v66, v66
	v_exp_f32_e32 v67, v67
	v_exp_f32_e32 v68, v68
	v_exp_f32_e32 v69, v69
	s_waitcnt lgkmcnt(2)
	v_mfma_f32_32x32x16_bf16 v[50:65], v[186:189], v[122:125], v[50:65]
	v_exp_f32_e32 v70, v70
	v_exp_f32_e32 v71, v71
	v_exp_f32_e32 v72, v72
	v_exp_f32_e32 v73, v73
	s_waitcnt lgkmcnt(0)
	v_mfma_f32_32x32x16_bf16 v[34:49], v[190:193], v[110:113], v[34:49]
	v_exp_f32_e32 v74, v74
	v_exp_f32_e32 v75, v75
	v_exp_f32_e32 v76, v76
	v_exp_f32_e32 v77, v77
	s_waitcnt lgkmcnt(0)
	v_mfma_f32_32x32x16_bf16 v[50:65], v[190:193], v[126:129], v[50:65]
	v_exp_f32_e32 v78, v78
	v_exp_f32_e32 v79, v79
	v_exp_f32_e32 v80, v80
	v_exp_f32_e32 v81, v81
	s_add_i32 s8, s14, 0x2000
	s_cmpk_lg_i32 s14, 0x6000
	s_cselect_b32 s14, s8, 0
	s_add_i32 s8, s16, 0x2000
	s_cmpk_lg_i32 s16, 0x6000
	s_cselect_b32 s16, s8, 0
	s_add_i32 s8, s15, 0x2000
	s_cmpk_lg_i32 s15, 0x6000
	s_cselect_b32 s15, s8, 0
	s_mov_b64 s[8:9], 0x4000
	s_add_u32 s20, s20, 0x4000
	s_addc_u32 s21, s21, 0
	s_add_u32 s22, s22, 0x4000
	s_addc_u32 s23, s23, 0
	s_cmpk_eq_i32 s13, 0x83
	s_cbranch_scc1 .LBB0_903

;   #define DMA_K(t,slot) glds16(ksrc+(long)(t)*KVBLK*kp,(unsigned)__builtin_amdgcn_readfirstlane(kdst+(slot)))
;   #define DMA_V(t,slot) glds16(vsrc+(long)(t)*KVBLK*vp,(unsigned)__builtin_amdgcn_readfirstlane(vdst+(slot)))
;   #define DMA_K(t,slot) glds16(ksrc+(long)(t)*KVBLK*kp,(unsigned)__builtin_amdgcn_readfirstlane(kdst+(slot)))
;   #define DMA_V(t,slot) glds16(vsrc+(long)(t)*KVBLK*vp,(unsigned)__builtin_amdgcn_readfirstlane(vdst+(slot)))
;   #define DMA_K(t,slot) glds16(ksrc+(long)(t)*KVBLK*kp,(unsigned)__builtin_amdgcn_readfirstlane(kdst+(slot)))
;   #define DMA_V(t,slot) do{ glds16(vsrc+(long)(t)*KVBLK*vp,(unsigned)__builtin_amdgcn_readfirstlane(vdst+2*(slot))); glds16(vsrc+64+(long)(t)*KVBLK*vp,(unsigned)__builtin_amdgcn_readfirstlane(vdst+2*(slot)+8192)); }while(0)
; __device__ __forceinline__ void attn_unit2(const bf16*Qu,int qp,const bf16*__restrict__ Kh,int kp,const bf16*__restrict__ Vh,int vp,bf16*Ou,int op,int NT,char*shm,int tid_in){
;     ...
;     if(t+3<NT){DMA_K(t+3,sl_n3);DMA_V(t+3,sl_n3);}
.LBB0_902:
	s_add_i32 s9, s15, s3
	s_mov_b32 s17, m0
	s_mov_b32 m0, s9
	s_nop 0
	global_load_lds_dwordx4 v228, s[20:21]
	s_mov_b32 m0, s17
	s_add_i32 s8, s15, s12
	s_mov_b32 s9, m0
	s_mov_b32 m0, s8
	s_nop 0
	global_load_lds_dwordx4 v230, s[22:23]
	s_mov_b32 m0, s9
	s_branch .LBB0_896
